# GEMM epilogues de-serialized: SwiGLU row-stat loads/shuffles batched; residual-update x loads hoisted 4 row-groups ahead with counted vmcnt (on top of MLA loop schedule)
# speedup vs baseline: 1.0183x; 1.0183x over previous
; #define EFENCE() asm volatile("" ::: "memory")
; DI float sq4(const f32x4& v) { return (v.x * v.x + v.y * v.y) + (v.z * v.z + v.w * v.w); }
; DI u32x4 pk8(const f32x4& a, const f32x4& b) { u32x4 w; w.x = cvtpk(a.x, a.y); w.y = cvtpk(a.z, a.w); w.z = cvtpk(b.x, b.y); w.w = cvtpk(b.z, b.w); return w; }
;     DI void operator()(AccRef acc, const Unit& u, int wr, int wc, int fr, int fq) const {
;     ...
;             for (int m = 0; m < 4; ++m) { if ((m & 1) == 0) EFENCE();
;                 const int row = EROW(u, ai, m); float ss = 0.f;
; #pragma unroll
;                 for (int bj = 0; bj < 2; ++bj) {
;                     const size_t off = (size_t)row * DM + u.pn * 256 + bj * 128 + wc * 32 + 8 * fq;
;                     f32x4 x0 = *(const f32x4*)(xin + off), x1 = *(const f32x4*)(xin + off + 4);
;                     x0 += acc[ai][bj][m][0] * alpha; x1 += acc[ai][bj][m][1] * alpha;
;                     *(f32x4*)(xout + off) = x0; *(f32x4*)(xout + off + 4) = x1;
;                     *(u32x4*)(xb + off) = pk8(x0, x1); ss += sq4(x0) + sq4(x1);
;                 }
.LBB1_995:
	v_mbcnt_lo_u32_b32 v0, -1, 0
	v_mbcnt_hi_u32_b32 v0, -1, v0
	s_lshl_b32 s30, s56, 8
	v_add_u32_e32 v0, s38, v0
	s_add_i32 s30, s30, s45
	s_nop 0
	v_and_or_b32 v130, v0, 15, s30
	s_lshl_b32 s30, s55, 8
	s_ashr_i32 s31, s30, 31
	v_bfe_u32 v131, v0, 4, 2
	s_or_b64 s[30:31], s[30:31], s[24:25]
	v_lshl_or_b32 v132, v131, 3, s30
	v_cmp_eq_u32_e32 vcc, 0, v131
	v_ashrrev_i32_e32 v131, 31, v130
	v_mov_b32_e32 v133, s31
	v_lshlrev_b64 v[134:135], 10, v[130:131]
	v_lshl_add_u64 v[142:143], v[132:133], 0, v[134:135]
	v_lshl_add_u64 v[144:145], v[142:143], 2, s[16:17]
	v_lshlrev_b32_e32 v240, 2, v142
	global_load_dwordx4 v[148:151], v240, s[16:17] offset:16
	global_load_dwordx4 v[152:155], v240, s[16:17] offset:0
	global_load_dwordx4 v[156:159], v240, s[16:17] offset:528
	global_load_dwordx4 v[160:163], v240, s[16:17] offset:512
	v_add_u32_e32 v242, 0x10000, v240
	global_load_dwordx4 v[164:167], v242, s[16:17] offset:16
	global_load_dwordx4 v[168:171], v242, s[16:17] offset:0
	global_load_dwordx4 v[172:175], v242, s[16:17] offset:528
	global_load_dwordx4 v[180:183], v242, s[16:17] offset:512
	v_add_u32_e32 v243, 0x20000, v240
	global_load_dwordx4 v[184:187], v243, s[16:17] offset:16
	global_load_dwordx4 v[188:191], v243, s[16:17] offset:0
	global_load_dwordx4 v[192:195], v243, s[16:17] offset:528
	global_load_dwordx4 v[196:199], v243, s[16:17] offset:512
	v_add_u32_e32 v241, 0x30000, v240
	global_load_dwordx4 v[200:203], v241, s[16:17] offset:16
	global_load_dwordx4 v[204:207], v241, s[16:17] offset:0
	global_load_dwordx4 v[208:211], v241, s[16:17] offset:528
	global_load_dwordx4 v[220:223], v241, s[16:17] offset:512
	s_lshl_b32 s30, s55, 2
	s_ashr_i32 s31, s30, 31
	s_waitcnt vmcnt(15)
	v_pk_add_f32 v[122:123], v[122:123], v[148:149]
	s_waitcnt vmcnt(14)
	v_pk_add_f32 v[128:129], v[128:129], v[154:155]
	v_pk_add_f32 v[126:127], v[126:127], v[152:153]
	v_pk_add_f32 v[124:125], v[124:125], v[150:151]
	global_store_dwordx4 v[144:145], v[126:129], off
	global_store_dwordx4 v[144:145], v[122:125], off offset:16
	v_cvt_pk_bf16_f32 v136, v122, v123
	v_mul_f32_e32 v0, v127, v127
	v_mul_f32_e32 v123, v123, v123
	v_cvt_pk_bf16_f32 v134, v126, v127
	v_lshlrev_b64 v[138:139], 1, v[142:143]
	v_fmac_f32_e32 v0, v126, v126
	v_mul_f32_e32 v126, v129, v129
	v_fmac_f32_e32 v123, v122, v122
	v_mul_f32_e32 v122, v125, v125
	v_cvt_pk_bf16_f32 v135, v128, v129
	v_cvt_pk_bf16_f32 v137, v124, v125
	v_lshl_add_u64 v[140:141], s[94:95], 0, v[138:139]
	v_fmac_f32_e32 v126, v128, v128
	v_fmac_f32_e32 v122, v124, v124
	global_store_dwordx4 v[140:141], v[134:137], off
	v_add_f32_e32 v0, v0, v126
	v_add_f32_e32 v122, v123, v122
	v_add_f32_e32 v0, v0, v122
	v_or_b32_e32 v138, 0x100, v138
	s_waitcnt vmcnt(16)
	v_pk_add_f32 v[114:115], v[114:115], v[156:157]
	s_waitcnt vmcnt(15)
	v_pk_add_f32 v[120:121], v[120:121], v[162:163]
	v_pk_add_f32 v[118:119], v[118:119], v[160:161]
	v_pk_add_f32 v[116:117], v[116:117], v[158:159]
	v_add_u32_e32 v242, 0x80000, v240
	global_load_dwordx4 v[148:151], v242, s[16:17] offset:16
	global_load_dwordx4 v[152:155], v242, s[16:17] offset:0
	global_load_dwordx4 v[156:159], v242, s[16:17] offset:528
	global_load_dwordx4 v[160:163], v242, s[16:17] offset:512
	global_store_dwordx4 v[144:145], v[118:121], off offset:512
	global_store_dwordx4 v[144:145], v[114:117], off offset:528
	v_cvt_pk_bf16_f32 v122, v118, v119
	v_cvt_pk_bf16_f32 v124, v114, v115
	v_mul_f32_e32 v119, v119, v119
	v_mul_f32_e32 v115, v115, v115
	v_fmac_f32_e32 v119, v118, v118
	v_mul_f32_e32 v118, v121, v121
	v_fmac_f32_e32 v115, v114, v114
	v_mul_f32_e32 v114, v117, v117
	v_fmac_f32_e32 v118, v120, v120
	v_fmac_f32_e32 v114, v116, v116
	v_add_f32_e32 v118, v119, v118
	v_add_f32_e32 v114, v115, v114
	v_cvt_pk_bf16_f32 v123, v120, v121
	v_cvt_pk_bf16_f32 v125, v116, v117
	v_lshl_add_u64 v[126:127], s[94:95], 0, v[138:139]
	v_add_f32_e32 v114, v118, v114
	global_store_dwordx4 v[126:127], v[122:125], off
	v_add_f32_e32 v0, v0, v114
	v_mbcnt_lo_u32_b32 v114, -1, 0
	v_mbcnt_hi_u32_b32 v114, -1, v114
	s_nop 0
	v_lshlrev_b32_e32 v114, 2, v114
	v_xor_b32_e32 v114, 64, v114
	ds_bpermute_b32 v114, v114, v0
	s_waitcnt lgkmcnt(0)
	v_add_f32_e32 v0, v0, v114
	v_mbcnt_lo_u32_b32 v114, -1, 0
	v_mbcnt_hi_u32_b32 v114, -1, v114
	s_nop 0
	v_lshlrev_b32_e32 v114, 2, v114
	v_xor_b32_e32 v114, 0x80, v114
	ds_bpermute_b32 v114, v114, v0
	s_and_saveexec_b64 s[34:35], vcc
	s_cbranch_execz .LBB1_997
	v_lshlrev_b64 v[116:117], 6, v[130:131]
	v_lshl_add_u64 v[116:117], s[96:97], 0, v[116:117]
	v_lshl_add_u64 v[116:117], s[30:31], 2, v[116:117]
	s_lshl_b32 s36, s44, 2
	s_mov_b32 s37, s76
	v_lshl_add_u64 v[116:117], v[116:117], 0, s[36:37]
	s_waitcnt lgkmcnt(0)
	v_add_f32_e32 v0, v0, v114
	global_store_dword v[116:117], v0, off
; #define EFENCE() asm volatile("" ::: "memory")
; DI float sum4q(float s) { s += shx(s, 16); s += shx(s, 32); return s; }
; DI float sq4(const f32x4& v) { return (v.x * v.x + v.y * v.y) + (v.z * v.z + v.w * v.w); }
; DI u32x4 pk8(const f32x4& a, const f32x4& b) { u32x4 w; w.x = cvtpk(a.x, a.y); w.y = cvtpk(a.z, a.w); w.z = cvtpk(b.x, b.y); w.w = cvtpk(b.z, b.w); return w; }
;     DI void operator()(AccRef acc, const Unit& u, int wr, int wc, int fr, int fq) const {
;     ...
;             for (int m = 0; m < 4; ++m) { if ((m & 1) == 0) EFENCE();
;                 const int row = EROW(u, ai, m); float ss = 0.f;
; #pragma unroll
;                 for (int bj = 0; bj < 2; ++bj) {
;                     const size_t off = (size_t)row * DM + u.pn * 256 + bj * 128 + wc * 32 + 8 * fq;
;                     f32x4 x0 = *(const f32x4*)(xin + off), x1 = *(const f32x4*)(xin + off + 4);
;                     x0 += acc[ai][bj][m][0] * alpha; x1 += acc[ai][bj][m][1] * alpha;
;                     *(f32x4*)(xout + off) = x0; *(f32x4*)(xout + off + 4) = x1;
;                     *(u32x4*)(xb + off) = pk8(x0, x1); ss += sq4(x0) + sq4(x1);
;                 }
;                 ss = sum4q(ss);
;                 if (fq == 0) ssq[(size_t)row * 16 + u.pn * 4 + wc] = ss;
.LBB1_997:
	s_or_b64 exec, exec, s[34:35]
	s_waitcnt lgkmcnt(0)
	v_or_b32_e32 v114, 16, v130
	v_ashrrev_i32_e32 v115, 31, v114
	v_lshlrev_b64 v[116:117], 10, v[114:115]
	v_lshl_add_u64 v[124:125], v[116:117], 0, v[132:133]
	v_lshl_add_u64 v[126:127], v[124:125], 2, s[16:17]
	s_waitcnt vmcnt(21)
	v_pk_add_f32 v[106:107], v[106:107], v[164:165]
	s_waitcnt vmcnt(20)
	v_pk_add_f32 v[112:113], v[112:113], v[170:171]
	v_pk_add_f32 v[110:111], v[110:111], v[168:169]
	v_pk_add_f32 v[108:109], v[108:109], v[166:167]
	global_store_dwordx4 v[126:127], v[110:113], off
	global_store_dwordx4 v[126:127], v[106:109], off offset:16
	v_cvt_pk_bf16_f32 v118, v106, v107
	v_mul_f32_e32 v0, v111, v111
	v_mul_f32_e32 v107, v107, v107
	v_cvt_pk_bf16_f32 v116, v110, v111
	v_lshlrev_b64 v[120:121], 1, v[124:125]
	v_fmac_f32_e32 v0, v110, v110
	v_mul_f32_e32 v110, v113, v113
	v_fmac_f32_e32 v107, v106, v106
	v_mul_f32_e32 v106, v109, v109
	v_cvt_pk_bf16_f32 v117, v112, v113
	v_cvt_pk_bf16_f32 v119, v108, v109
	v_lshl_add_u64 v[122:123], s[94:95], 0, v[120:121]
	v_fmac_f32_e32 v110, v112, v112
	v_fmac_f32_e32 v106, v108, v108
	global_store_dwordx4 v[122:123], v[116:119], off
	v_add_f32_e32 v0, v0, v110
	v_add_f32_e32 v106, v107, v106
	v_add_f32_e32 v0, v0, v106
	v_or_b32_e32 v120, 0x100, v120
	s_waitcnt vmcnt(22)
	v_pk_add_f32 v[98:99], v[98:99], v[172:173]
	s_waitcnt vmcnt(21)
	v_pk_add_f32 v[104:105], v[104:105], v[182:183]
	v_pk_add_f32 v[102:103], v[102:103], v[180:181]
	v_pk_add_f32 v[100:101], v[100:101], v[174:175]
	v_add_u32_e32 v243, 0x90000, v240
	global_load_dwordx4 v[164:167], v243, s[16:17] offset:16
	global_load_dwordx4 v[168:171], v243, s[16:17] offset:0
	global_load_dwordx4 v[172:175], v243, s[16:17] offset:528
	global_load_dwordx4 v[180:183], v243, s[16:17] offset:512
	global_store_dwordx4 v[126:127], v[102:105], off offset:512
	global_store_dwordx4 v[126:127], v[98:101], off offset:528
	v_cvt_pk_bf16_f32 v106, v102, v103
	v_cvt_pk_bf16_f32 v108, v98, v99
	v_mul_f32_e32 v103, v103, v103
	v_mul_f32_e32 v99, v99, v99
	v_fmac_f32_e32 v103, v102, v102
	v_mul_f32_e32 v102, v105, v105
	v_fmac_f32_e32 v99, v98, v98
	v_mul_f32_e32 v98, v101, v101
	v_fmac_f32_e32 v102, v104, v104
	v_fmac_f32_e32 v98, v100, v100
	v_add_f32_e32 v102, v103, v102
	v_add_f32_e32 v98, v99, v98
	v_cvt_pk_bf16_f32 v107, v104, v105
	v_cvt_pk_bf16_f32 v109, v100, v101
	v_lshl_add_u64 v[110:111], s[94:95], 0, v[120:121]
	v_add_f32_e32 v98, v102, v98
	global_store_dwordx4 v[110:111], v[106:109], off
	v_add_f32_e32 v0, v0, v98
	v_mbcnt_lo_u32_b32 v98, -1, 0
	v_mbcnt_hi_u32_b32 v98, -1, v98
	s_nop 0
	v_lshlrev_b32_e32 v98, 2, v98
	v_xor_b32_e32 v98, 64, v98
	ds_bpermute_b32 v98, v98, v0
	s_waitcnt lgkmcnt(0)
	v_add_f32_e32 v0, v0, v98
	v_mbcnt_lo_u32_b32 v98, -1, 0
	v_mbcnt_hi_u32_b32 v98, -1, v98
	s_nop 0
	v_lshlrev_b32_e32 v98, 2, v98
	v_xor_b32_e32 v98, 0x80, v98
	ds_bpermute_b32 v98, v98, v0
	s_and_saveexec_b64 s[34:35], vcc
	s_cbranch_execz .LBB1_999
	v_lshlrev_b64 v[100:101], 6, v[114:115]
	v_lshl_add_u64 v[100:101], s[96:97], 0, v[100:101]
	v_lshl_add_u64 v[100:101], s[30:31], 2, v[100:101]
	s_lshl_b32 s36, s44, 2
	s_mov_b32 s37, s76
	v_lshl_add_u64 v[100:101], v[100:101], 0, s[36:37]
	s_waitcnt lgkmcnt(0)
	v_add_f32_e32 v0, v0, v98
	global_store_dword v[100:101], v0, off
.LBB1_999:
	s_or_b64 exec, exec, s[34:35]
	s_waitcnt lgkmcnt(0)
	v_or_b32_e32 v98, 32, v130
	v_ashrrev_i32_e32 v99, 31, v98
	v_lshlrev_b64 v[100:101], 10, v[98:99]
	v_lshl_add_u64 v[108:109], v[100:101], 0, v[132:133]
	v_lshl_add_u64 v[110:111], v[108:109], 2, s[16:17]
	s_waitcnt vmcnt(27)
	v_pk_add_f32 v[90:91], v[90:91], v[184:185]
	s_waitcnt vmcnt(26)
	v_pk_add_f32 v[96:97], v[96:97], v[190:191]
	v_pk_add_f32 v[94:95], v[94:95], v[188:189]
	v_pk_add_f32 v[92:93], v[92:93], v[186:187]
	global_store_dwordx4 v[110:111], v[94:97], off
	global_store_dwordx4 v[110:111], v[90:93], off offset:16
	v_cvt_pk_bf16_f32 v102, v90, v91
	v_mul_f32_e32 v0, v95, v95
	v_mul_f32_e32 v91, v91, v91
	v_cvt_pk_bf16_f32 v100, v94, v95
	v_lshlrev_b64 v[104:105], 1, v[108:109]
	v_fmac_f32_e32 v0, v94, v94
	v_mul_f32_e32 v94, v97, v97
	v_fmac_f32_e32 v91, v90, v90
	v_mul_f32_e32 v90, v93, v93
	v_cvt_pk_bf16_f32 v101, v96, v97
	v_cvt_pk_bf16_f32 v103, v92, v93
	v_lshl_add_u64 v[106:107], s[94:95], 0, v[104:105]
	v_fmac_f32_e32 v94, v96, v96
	v_fmac_f32_e32 v90, v92, v92
	global_store_dwordx4 v[106:107], v[100:103], off
	v_add_f32_e32 v0, v0, v94
	v_add_f32_e32 v90, v91, v90
	v_add_f32_e32 v0, v0, v90
	v_or_b32_e32 v104, 0x100, v104
	s_waitcnt vmcnt(28)
	v_pk_add_f32 v[82:83], v[82:83], v[192:193]
	s_waitcnt vmcnt(27)
	v_pk_add_f32 v[88:89], v[88:89], v[198:199]
	v_pk_add_f32 v[86:87], v[86:87], v[196:197]
	v_pk_add_f32 v[84:85], v[84:85], v[194:195]
	v_add_u32_e32 v241, 0xa0000, v240
	global_load_dwordx4 v[184:187], v241, s[16:17] offset:16
	global_load_dwordx4 v[188:191], v241, s[16:17] offset:0
	global_load_dwordx4 v[192:195], v241, s[16:17] offset:528
	global_load_dwordx4 v[196:199], v241, s[16:17] offset:512
	global_store_dwordx4 v[110:111], v[86:89], off offset:512
	global_store_dwordx4 v[110:111], v[82:85], off offset:528
	v_cvt_pk_bf16_f32 v90, v86, v87
	v_cvt_pk_bf16_f32 v92, v82, v83
	v_mul_f32_e32 v87, v87, v87
	v_mul_f32_e32 v83, v83, v83
	v_fmac_f32_e32 v87, v86, v86
	v_mul_f32_e32 v86, v89, v89
	v_fmac_f32_e32 v83, v82, v82
	v_mul_f32_e32 v82, v85, v85
	v_fmac_f32_e32 v86, v88, v88
	v_fmac_f32_e32 v82, v84, v84
	v_add_f32_e32 v86, v87, v86
	v_add_f32_e32 v82, v83, v82
	v_cvt_pk_bf16_f32 v91, v88, v89
	v_cvt_pk_bf16_f32 v93, v84, v85
	v_lshl_add_u64 v[94:95], s[94:95], 0, v[104:105]
	v_add_f32_e32 v82, v86, v82
	global_store_dwordx4 v[94:95], v[90:93], off
	v_add_f32_e32 v0, v0, v82
	v_mbcnt_lo_u32_b32 v82, -1, 0
	v_mbcnt_hi_u32_b32 v82, -1, v82
	s_nop 0
	v_lshlrev_b32_e32 v82, 2, v82
	v_xor_b32_e32 v82, 64, v82
	ds_bpermute_b32 v82, v82, v0
	s_waitcnt lgkmcnt(0)
	v_add_f32_e32 v0, v0, v82
	v_mbcnt_lo_u32_b32 v82, -1, 0
	v_mbcnt_hi_u32_b32 v82, -1, v82
	s_nop 0
	v_lshlrev_b32_e32 v82, 2, v82
	v_xor_b32_e32 v82, 0x80, v82
	ds_bpermute_b32 v82, v82, v0
	s_and_saveexec_b64 s[34:35], vcc
	s_cbranch_execz .LBB1_1001
	v_lshlrev_b64 v[84:85], 6, v[98:99]
	v_lshl_add_u64 v[84:85], s[96:97], 0, v[84:85]
	v_lshl_add_u64 v[84:85], s[30:31], 2, v[84:85]
	s_lshl_b32 s36, s44, 2
	s_mov_b32 s37, s76
	v_lshl_add_u64 v[84:85], v[84:85], 0, s[36:37]
	s_waitcnt lgkmcnt(0)
	v_add_f32_e32 v0, v0, v82
	global_store_dword v[84:85], v0, off
; #define EFENCE() asm volatile("" ::: "memory")
; DI float sum4q(float s) { s += shx(s, 16); s += shx(s, 32); return s; }
; DI float sq4(const f32x4& v) { return (v.x * v.x + v.y * v.y) + (v.z * v.z + v.w * v.w); }
; DI u32x4 pk8(const f32x4& a, const f32x4& b) { u32x4 w; w.x = cvtpk(a.x, a.y); w.y = cvtpk(a.z, a.w); w.z = cvtpk(b.x, b.y); w.w = cvtpk(b.z, b.w); return w; }
;     DI void operator()(AccRef acc, const Unit& u, int wr, int wc, int fr, int fq) const {
;     ...
;             for (int m = 0; m < 4; ++m) { if ((m & 1) == 0) EFENCE();
;                 const int row = EROW(u, ai, m); float ss = 0.f;
; #pragma unroll
;                 for (int bj = 0; bj < 2; ++bj) {
;                     const size_t off = (size_t)row * DM + u.pn * 256 + bj * 128 + wc * 32 + 8 * fq;
;                     f32x4 x0 = *(const f32x4*)(xin + off), x1 = *(const f32x4*)(xin + off + 4);
;                     x0 += acc[ai][bj][m][0] * alpha; x1 += acc[ai][bj][m][1] * alpha;
;                     *(f32x4*)(xout + off) = x0; *(f32x4*)(xout + off + 4) = x1;
;                     *(u32x4*)(xb + off) = pk8(x0, x1); ss += sq4(x0) + sq4(x1);
;                 }
;                 ss = sum4q(ss);
;                 if (fq == 0) ssq[(size_t)row * 16 + u.pn * 4 + wc] = ss;
.LBB1_1001:
	s_or_b64 exec, exec, s[34:35]
	s_waitcnt lgkmcnt(0)
	v_or_b32_e32 v82, 48, v130
	v_ashrrev_i32_e32 v83, 31, v82
	v_lshlrev_b64 v[84:85], 10, v[82:83]
	v_lshl_add_u64 v[92:93], v[84:85], 0, v[132:133]
	v_lshl_add_u64 v[94:95], v[92:93], 2, s[16:17]
	s_waitcnt vmcnt(33)
	v_pk_add_f32 v[74:75], v[74:75], v[200:201]
	s_waitcnt vmcnt(32)
	v_pk_add_f32 v[80:81], v[80:81], v[206:207]
	v_pk_add_f32 v[78:79], v[78:79], v[204:205]
	v_pk_add_f32 v[76:77], v[76:77], v[202:203]
	global_store_dwordx4 v[94:95], v[78:81], off
	global_store_dwordx4 v[94:95], v[74:77], off offset:16
	v_cvt_pk_bf16_f32 v86, v74, v75
	v_mul_f32_e32 v0, v79, v79
	v_mul_f32_e32 v75, v75, v75
	v_cvt_pk_bf16_f32 v84, v78, v79
	v_lshlrev_b64 v[88:89], 1, v[92:93]
	v_fmac_f32_e32 v0, v78, v78
	v_mul_f32_e32 v78, v81, v81
	v_fmac_f32_e32 v75, v74, v74
	v_mul_f32_e32 v74, v77, v77
	v_cvt_pk_bf16_f32 v85, v80, v81
	v_cvt_pk_bf16_f32 v87, v76, v77
	v_lshl_add_u64 v[90:91], s[94:95], 0, v[88:89]
	v_fmac_f32_e32 v78, v80, v80
	v_fmac_f32_e32 v74, v76, v76
	global_store_dwordx4 v[90:91], v[84:87], off
	v_add_f32_e32 v0, v0, v78
	v_add_f32_e32 v74, v75, v74
	v_add_f32_e32 v0, v0, v74
	v_or_b32_e32 v88, 0x100, v88
	s_waitcnt vmcnt(34)
	v_pk_add_f32 v[66:67], v[66:67], v[208:209]
	s_waitcnt vmcnt(33)
	v_pk_add_f32 v[72:73], v[72:73], v[222:223]
	v_pk_add_f32 v[70:71], v[70:71], v[220:221]
	v_pk_add_f32 v[68:69], v[68:69], v[210:211]
	v_add_u32_e32 v242, 0xb0000, v240
	global_load_dwordx4 v[200:203], v242, s[16:17] offset:16
	global_load_dwordx4 v[204:207], v242, s[16:17] offset:0
	global_load_dwordx4 v[208:211], v242, s[16:17] offset:528
	global_load_dwordx4 v[220:223], v242, s[16:17] offset:512
	global_store_dwordx4 v[94:95], v[70:73], off offset:512
	global_store_dwordx4 v[94:95], v[66:69], off offset:528
	v_cvt_pk_bf16_f32 v74, v70, v71
	v_cvt_pk_bf16_f32 v76, v66, v67
	v_mul_f32_e32 v71, v71, v71
	v_mul_f32_e32 v67, v67, v67
	v_fmac_f32_e32 v71, v70, v70
	v_mul_f32_e32 v70, v73, v73
	v_fmac_f32_e32 v67, v66, v66
	v_mul_f32_e32 v66, v69, v69
	v_fmac_f32_e32 v70, v72, v72
	v_fmac_f32_e32 v66, v68, v68
	v_add_f32_e32 v70, v71, v70
	v_add_f32_e32 v66, v67, v66
	v_cvt_pk_bf16_f32 v75, v72, v73
	v_cvt_pk_bf16_f32 v77, v68, v69
	v_lshl_add_u64 v[78:79], s[94:95], 0, v[88:89]
	v_add_f32_e32 v66, v70, v66
	global_store_dwordx4 v[78:79], v[74:77], off
	v_add_f32_e32 v0, v0, v66
	v_mbcnt_lo_u32_b32 v66, -1, 0
	v_mbcnt_hi_u32_b32 v66, -1, v66
	s_nop 0
	v_lshlrev_b32_e32 v66, 2, v66
	v_xor_b32_e32 v66, 64, v66
	ds_bpermute_b32 v66, v66, v0
	s_waitcnt lgkmcnt(0)
	v_add_f32_e32 v0, v0, v66
	v_mbcnt_lo_u32_b32 v66, -1, 0
	v_mbcnt_hi_u32_b32 v66, -1, v66
	s_nop 0
	v_lshlrev_b32_e32 v66, 2, v66
	v_xor_b32_e32 v66, 0x80, v66
	ds_bpermute_b32 v66, v66, v0
	s_and_saveexec_b64 s[34:35], vcc
	s_cbranch_execz .LBB1_1003
	v_lshlrev_b64 v[68:69], 6, v[82:83]
	v_lshl_add_u64 v[68:69], s[96:97], 0, v[68:69]
	v_lshl_add_u64 v[68:69], s[30:31], 2, v[68:69]
	s_lshl_b32 s36, s44, 2
	s_mov_b32 s37, s76
	v_lshl_add_u64 v[68:69], v[68:69], 0, s[36:37]
	s_waitcnt lgkmcnt(0)
	v_add_f32_e32 v0, v0, v66
	global_store_dword v[68:69], v0, off
.LBB1_1003:
	s_or_b64 exec, exec, s[34:35]
	s_waitcnt lgkmcnt(0)
	v_add_u32_e32 v66, 0x80, v130
	v_ashrrev_i32_e32 v67, 31, v66
	v_lshlrev_b64 v[68:69], 10, v[66:67]
	v_lshl_add_u64 v[76:77], v[68:69], 0, v[132:133]
	v_lshl_add_u64 v[78:79], v[76:77], 2, s[16:17]
	s_waitcnt vmcnt(36)
	v_pk_add_f32 v[58:59], v[58:59], v[148:149]
	s_waitcnt vmcnt(35)
	v_pk_add_f32 v[64:65], v[64:65], v[154:155]
	v_pk_add_f32 v[62:63], v[62:63], v[152:153]
	v_pk_add_f32 v[60:61], v[60:61], v[150:151]
	global_store_dwordx4 v[78:79], v[62:65], off
	global_store_dwordx4 v[78:79], v[58:61], off offset:16
	v_cvt_pk_bf16_f32 v70, v58, v59
	v_mul_f32_e32 v0, v63, v63
	v_mul_f32_e32 v59, v59, v59
	v_cvt_pk_bf16_f32 v68, v62, v63
	v_lshlrev_b64 v[72:73], 1, v[76:77]
	v_fmac_f32_e32 v0, v62, v62
	v_mul_f32_e32 v62, v65, v65
	v_fmac_f32_e32 v59, v58, v58
	v_mul_f32_e32 v58, v61, v61
	v_cvt_pk_bf16_f32 v69, v64, v65
	v_cvt_pk_bf16_f32 v71, v60, v61
	v_lshl_add_u64 v[74:75], s[94:95], 0, v[72:73]
	v_fmac_f32_e32 v62, v64, v64
	v_fmac_f32_e32 v58, v60, v60
	global_store_dwordx4 v[74:75], v[68:71], off
	v_add_f32_e32 v0, v0, v62
	v_add_f32_e32 v58, v59, v58
	v_add_f32_e32 v0, v0, v58
	v_or_b32_e32 v72, 0x100, v72
	s_waitcnt vmcnt(37)
	v_pk_add_f32 v[50:51], v[50:51], v[156:157]
	s_waitcnt vmcnt(36)
	v_pk_add_f32 v[56:57], v[56:57], v[162:163]
	v_pk_add_f32 v[54:55], v[54:55], v[160:161]
	v_pk_add_f32 v[52:53], v[52:53], v[158:159]
	global_store_dwordx4 v[78:79], v[54:57], off offset:512
	global_store_dwordx4 v[78:79], v[50:53], off offset:528
	v_cvt_pk_bf16_f32 v58, v54, v55
	v_cvt_pk_bf16_f32 v60, v50, v51
	v_mul_f32_e32 v55, v55, v55
	v_mul_f32_e32 v51, v51, v51
	v_fmac_f32_e32 v55, v54, v54
	v_mul_f32_e32 v54, v57, v57
	v_fmac_f32_e32 v51, v50, v50
	v_mul_f32_e32 v50, v53, v53
	v_fmac_f32_e32 v54, v56, v56
	v_fmac_f32_e32 v50, v52, v52
	v_add_f32_e32 v54, v55, v54
	v_add_f32_e32 v50, v51, v50
	v_cvt_pk_bf16_f32 v59, v56, v57
	v_cvt_pk_bf16_f32 v61, v52, v53
	v_lshl_add_u64 v[62:63], s[94:95], 0, v[72:73]
	v_add_f32_e32 v50, v54, v50
	global_store_dwordx4 v[62:63], v[58:61], off
	v_add_f32_e32 v0, v0, v50
	v_mbcnt_lo_u32_b32 v50, -1, 0
	v_mbcnt_hi_u32_b32 v50, -1, v50
	s_nop 0
	v_lshlrev_b32_e32 v50, 2, v50
	v_xor_b32_e32 v50, 64, v50
	ds_bpermute_b32 v50, v50, v0
	s_waitcnt lgkmcnt(0)
	v_add_f32_e32 v0, v0, v50
	v_mbcnt_lo_u32_b32 v50, -1, 0
	v_mbcnt_hi_u32_b32 v50, -1, v50
	s_nop 0
	v_lshlrev_b32_e32 v50, 2, v50
	v_xor_b32_e32 v50, 0x80, v50
	ds_bpermute_b32 v50, v50, v0
	s_and_saveexec_b64 s[34:35], vcc
	s_cbranch_execz .LBB1_1005
	v_lshlrev_b64 v[52:53], 6, v[66:67]
	v_lshl_add_u64 v[52:53], s[96:97], 0, v[52:53]
	v_lshl_add_u64 v[52:53], s[30:31], 2, v[52:53]
	s_lshl_b32 s36, s44, 2
	s_mov_b32 s37, s76
	v_lshl_add_u64 v[52:53], v[52:53], 0, s[36:37]
	s_waitcnt lgkmcnt(0)
	v_add_f32_e32 v0, v0, v50
	global_store_dword v[52:53], v0, off
; #define EFENCE() asm volatile("" ::: "memory")
; DI float sum4q(float s) { s += shx(s, 16); s += shx(s, 32); return s; }
; DI float sq4(const f32x4& v) { return (v.x * v.x + v.y * v.y) + (v.z * v.z + v.w * v.w); }
; DI u32x4 pk8(const f32x4& a, const f32x4& b) { u32x4 w; w.x = cvtpk(a.x, a.y); w.y = cvtpk(a.z, a.w); w.z = cvtpk(b.x, b.y); w.w = cvtpk(b.z, b.w); return w; }
;     DI void operator()(AccRef acc, const Unit& u, int wr, int wc, int fr, int fq) const {
;     ...
;             for (int m = 0; m < 4; ++m) { if ((m & 1) == 0) EFENCE();
;                 const int row = EROW(u, ai, m); float ss = 0.f;
; #pragma unroll
;                 for (int bj = 0; bj < 2; ++bj) {
;                     const size_t off = (size_t)row * DM + u.pn * 256 + bj * 128 + wc * 32 + 8 * fq;
;                     f32x4 x0 = *(const f32x4*)(xin + off), x1 = *(const f32x4*)(xin + off + 4);
;                     x0 += acc[ai][bj][m][0] * alpha; x1 += acc[ai][bj][m][1] * alpha;
;                     *(f32x4*)(xout + off) = x0; *(f32x4*)(xout + off + 4) = x1;
;                     *(u32x4*)(xb + off) = pk8(x0, x1); ss += sq4(x0) + sq4(x1);
;                 }
;                 ss = sum4q(ss);
;                 if (fq == 0) ssq[(size_t)row * 16 + u.pn * 4 + wc] = ss;
.LBB1_1005:
	s_or_b64 exec, exec, s[34:35]
	s_waitcnt lgkmcnt(0)
	v_add_u32_e32 v50, 0x90, v130
	v_ashrrev_i32_e32 v51, 31, v50
	v_lshlrev_b64 v[52:53], 10, v[50:51]
	v_lshl_add_u64 v[60:61], v[52:53], 0, v[132:133]
	v_lshl_add_u64 v[62:63], v[60:61], 2, s[16:17]
	s_waitcnt vmcnt(32)
	v_pk_add_f32 v[42:43], v[42:43], v[164:165]
	s_waitcnt vmcnt(31)
	v_pk_add_f32 v[48:49], v[48:49], v[170:171]
	v_pk_add_f32 v[46:47], v[46:47], v[168:169]
	v_pk_add_f32 v[44:45], v[44:45], v[166:167]
	global_store_dwordx4 v[62:63], v[46:49], off
	global_store_dwordx4 v[62:63], v[42:45], off offset:16
	v_cvt_pk_bf16_f32 v54, v42, v43
	v_mul_f32_e32 v0, v47, v47
	v_mul_f32_e32 v43, v43, v43
	v_cvt_pk_bf16_f32 v52, v46, v47
	v_lshlrev_b64 v[56:57], 1, v[60:61]
	v_fmac_f32_e32 v0, v46, v46
	v_mul_f32_e32 v46, v49, v49
	v_fmac_f32_e32 v43, v42, v42
	v_mul_f32_e32 v42, v45, v45
	v_cvt_pk_bf16_f32 v53, v48, v49
	v_cvt_pk_bf16_f32 v55, v44, v45
	v_lshl_add_u64 v[58:59], s[94:95], 0, v[56:57]
	v_fmac_f32_e32 v46, v48, v48
	v_fmac_f32_e32 v42, v44, v44
	global_store_dwordx4 v[58:59], v[52:55], off
	v_add_f32_e32 v0, v0, v46
	v_add_f32_e32 v42, v43, v42
	v_add_f32_e32 v0, v0, v42
	v_or_b32_e32 v56, 0x100, v56
	s_waitcnt vmcnt(33)
	v_pk_add_f32 v[34:35], v[34:35], v[172:173]
	s_waitcnt vmcnt(32)
	v_pk_add_f32 v[40:41], v[40:41], v[182:183]
	v_pk_add_f32 v[38:39], v[38:39], v[180:181]
	v_pk_add_f32 v[36:37], v[36:37], v[174:175]
	global_store_dwordx4 v[62:63], v[38:41], off offset:512
	global_store_dwordx4 v[62:63], v[34:37], off offset:528
	v_cvt_pk_bf16_f32 v42, v38, v39
	v_cvt_pk_bf16_f32 v44, v34, v35
	v_mul_f32_e32 v39, v39, v39
	v_mul_f32_e32 v35, v35, v35
	v_fmac_f32_e32 v39, v38, v38
	v_mul_f32_e32 v38, v41, v41
	v_fmac_f32_e32 v35, v34, v34
	v_mul_f32_e32 v34, v37, v37
	v_fmac_f32_e32 v38, v40, v40
	v_fmac_f32_e32 v34, v36, v36
	v_add_f32_e32 v38, v39, v38
	v_add_f32_e32 v34, v35, v34
	v_cvt_pk_bf16_f32 v43, v40, v41
	v_cvt_pk_bf16_f32 v45, v36, v37
	v_lshl_add_u64 v[46:47], s[94:95], 0, v[56:57]
	v_add_f32_e32 v34, v38, v34
	global_store_dwordx4 v[46:47], v[42:45], off
	v_add_f32_e32 v0, v0, v34
	v_mbcnt_lo_u32_b32 v34, -1, 0
	v_mbcnt_hi_u32_b32 v34, -1, v34
	s_nop 0
	v_lshlrev_b32_e32 v34, 2, v34
	v_xor_b32_e32 v34, 64, v34
	ds_bpermute_b32 v34, v34, v0
	s_waitcnt lgkmcnt(0)
	v_add_f32_e32 v0, v0, v34
	v_mbcnt_lo_u32_b32 v34, -1, 0
	v_mbcnt_hi_u32_b32 v34, -1, v34
	s_nop 0
	v_lshlrev_b32_e32 v34, 2, v34
	v_xor_b32_e32 v34, 0x80, v34
	ds_bpermute_b32 v34, v34, v0
	s_and_saveexec_b64 s[34:35], vcc
	s_cbranch_execz .LBB1_1007
	v_lshlrev_b64 v[36:37], 6, v[50:51]
	v_lshl_add_u64 v[36:37], s[96:97], 0, v[36:37]
	v_lshl_add_u64 v[36:37], s[30:31], 2, v[36:37]
	s_lshl_b32 s36, s44, 2
	s_mov_b32 s37, s76
	v_lshl_add_u64 v[36:37], v[36:37], 0, s[36:37]
	s_waitcnt lgkmcnt(0)
	v_add_f32_e32 v0, v0, v34
	global_store_dword v[36:37], v0, off
; #define EFENCE() asm volatile("" ::: "memory")
; DI float sum4q(float s) { s += shx(s, 16); s += shx(s, 32); return s; }
; DI float sq4(const f32x4& v) { return (v.x * v.x + v.y * v.y) + (v.z * v.z + v.w * v.w); }
; DI u32x4 pk8(const f32x4& a, const f32x4& b) { u32x4 w; w.x = cvtpk(a.x, a.y); w.y = cvtpk(a.z, a.w); w.z = cvtpk(b.x, b.y); w.w = cvtpk(b.z, b.w); return w; }
;     DI void operator()(AccRef acc, const Unit& u, int wr, int wc, int fr, int fq) const {
;     ...
;             for (int m = 0; m < 4; ++m) { if ((m & 1) == 0) EFENCE();
;                 const int row = EROW(u, ai, m); float ss = 0.f;
; #pragma unroll
;                 for (int bj = 0; bj < 2; ++bj) {
;                     const size_t off = (size_t)row * DM + u.pn * 256 + bj * 128 + wc * 32 + 8 * fq;
;                     f32x4 x0 = *(const f32x4*)(xin + off), x1 = *(const f32x4*)(xin + off + 4);
;                     x0 += acc[ai][bj][m][0] * alpha; x1 += acc[ai][bj][m][1] * alpha;
;                     *(f32x4*)(xout + off) = x0; *(f32x4*)(xout + off + 4) = x1;
;                     *(u32x4*)(xb + off) = pk8(x0, x1); ss += sq4(x0) + sq4(x1);
;                 }
;                 ss = sum4q(ss);
;                 if (fq == 0) ssq[(size_t)row * 16 + u.pn * 4 + wc] = ss;
.LBB1_1007:
	s_or_b64 exec, exec, s[34:35]
	s_waitcnt lgkmcnt(0)
	v_add_u32_e32 v34, 0xa0, v130
	v_ashrrev_i32_e32 v35, 31, v34
	v_lshlrev_b64 v[36:37], 10, v[34:35]
	v_lshl_add_u64 v[44:45], v[36:37], 0, v[132:133]
	v_lshl_add_u64 v[46:47], v[44:45], 2, s[16:17]
	s_waitcnt vmcnt(28)
	v_pk_add_f32 v[26:27], v[26:27], v[184:185]
	s_waitcnt vmcnt(27)
	v_pk_add_f32 v[32:33], v[32:33], v[190:191]
	v_pk_add_f32 v[30:31], v[30:31], v[188:189]
	v_pk_add_f32 v[28:29], v[28:29], v[186:187]
	global_store_dwordx4 v[46:47], v[30:33], off
	global_store_dwordx4 v[46:47], v[26:29], off offset:16
	v_cvt_pk_bf16_f32 v38, v26, v27
	v_mul_f32_e32 v0, v31, v31
	v_mul_f32_e32 v27, v27, v27
	v_cvt_pk_bf16_f32 v36, v30, v31
	v_lshlrev_b64 v[40:41], 1, v[44:45]
	v_fmac_f32_e32 v0, v30, v30
	v_mul_f32_e32 v30, v33, v33
	v_fmac_f32_e32 v27, v26, v26
	v_mul_f32_e32 v26, v29, v29
	v_cvt_pk_bf16_f32 v37, v32, v33
	v_cvt_pk_bf16_f32 v39, v28, v29
	v_lshl_add_u64 v[42:43], s[94:95], 0, v[40:41]
	v_fmac_f32_e32 v30, v32, v32
	v_fmac_f32_e32 v26, v28, v28
	global_store_dwordx4 v[42:43], v[36:39], off
	v_add_f32_e32 v0, v0, v30
	v_add_f32_e32 v26, v27, v26
	v_add_f32_e32 v0, v0, v26
	v_or_b32_e32 v40, 0x100, v40
	s_waitcnt vmcnt(29)
	v_pk_add_f32 v[18:19], v[18:19], v[192:193]
	s_waitcnt vmcnt(28)
	v_pk_add_f32 v[24:25], v[24:25], v[198:199]
	v_pk_add_f32 v[22:23], v[22:23], v[196:197]
	v_pk_add_f32 v[20:21], v[20:21], v[194:195]
	global_store_dwordx4 v[46:47], v[22:25], off offset:512
	global_store_dwordx4 v[46:47], v[18:21], off offset:528
	v_cvt_pk_bf16_f32 v26, v22, v23
	v_cvt_pk_bf16_f32 v28, v18, v19
	v_mul_f32_e32 v23, v23, v23
	v_mul_f32_e32 v19, v19, v19
	v_fmac_f32_e32 v23, v22, v22
	v_mul_f32_e32 v22, v25, v25
	v_fmac_f32_e32 v19, v18, v18
	v_mul_f32_e32 v18, v21, v21
	v_fmac_f32_e32 v22, v24, v24
	v_fmac_f32_e32 v18, v20, v20
	v_add_f32_e32 v22, v23, v22
	v_add_f32_e32 v18, v19, v18
	v_cvt_pk_bf16_f32 v27, v24, v25
	v_cvt_pk_bf16_f32 v29, v20, v21
	v_lshl_add_u64 v[30:31], s[94:95], 0, v[40:41]
	v_add_f32_e32 v18, v22, v18
	global_store_dwordx4 v[30:31], v[26:29], off
	v_add_f32_e32 v0, v0, v18
	v_mbcnt_lo_u32_b32 v18, -1, 0
	v_mbcnt_hi_u32_b32 v18, -1, v18
	s_nop 0
	v_lshlrev_b32_e32 v18, 2, v18
	v_xor_b32_e32 v18, 64, v18
	ds_bpermute_b32 v18, v18, v0
	s_waitcnt lgkmcnt(0)
	v_add_f32_e32 v0, v0, v18
	v_mbcnt_lo_u32_b32 v18, -1, 0
	v_mbcnt_hi_u32_b32 v18, -1, v18
	s_nop 0
	v_lshlrev_b32_e32 v18, 2, v18
	v_xor_b32_e32 v18, 0x80, v18
	ds_bpermute_b32 v18, v18, v0
	s_and_saveexec_b64 s[34:35], vcc
	s_cbranch_execz .LBB1_1009
	v_lshlrev_b64 v[20:21], 6, v[34:35]
	v_lshl_add_u64 v[20:21], s[96:97], 0, v[20:21]
	v_lshl_add_u64 v[20:21], s[30:31], 2, v[20:21]
	s_lshl_b32 s36, s44, 2
	s_mov_b32 s37, s76
	v_lshl_add_u64 v[20:21], v[20:21], 0, s[36:37]
	s_waitcnt lgkmcnt(0)
	v_add_f32_e32 v0, v0, v18
	global_store_dword v[20:21], v0, off
.LBB1_1009:
	s_or_b64 exec, exec, s[34:35]
	s_waitcnt lgkmcnt(0)
	v_add_u32_e32 v18, 0xb0, v130
	v_ashrrev_i32_e32 v19, 31, v18
	v_lshlrev_b64 v[20:21], 10, v[18:19]
	v_lshl_add_u64 v[28:29], v[20:21], 0, v[132:133]
	v_lshl_add_u64 v[30:31], v[28:29], 2, s[16:17]
	s_waitcnt vmcnt(24)
	v_pk_add_f32 v[10:11], v[10:11], v[200:201]
	s_waitcnt vmcnt(23)
	v_pk_add_f32 v[16:17], v[16:17], v[206:207]
	v_pk_add_f32 v[14:15], v[14:15], v[204:205]
	v_pk_add_f32 v[12:13], v[12:13], v[202:203]
	global_store_dwordx4 v[30:31], v[14:17], off
	global_store_dwordx4 v[30:31], v[10:13], off offset:16
	v_cvt_pk_bf16_f32 v22, v10, v11
	v_mul_f32_e32 v0, v15, v15
	v_mul_f32_e32 v11, v11, v11
	v_cvt_pk_bf16_f32 v20, v14, v15
	v_lshlrev_b64 v[24:25], 1, v[28:29]
	v_fmac_f32_e32 v0, v14, v14
	v_mul_f32_e32 v14, v17, v17
	v_fmac_f32_e32 v11, v10, v10
	v_mul_f32_e32 v10, v13, v13
	v_cvt_pk_bf16_f32 v21, v16, v17
	v_cvt_pk_bf16_f32 v23, v12, v13
	v_lshl_add_u64 v[26:27], s[94:95], 0, v[24:25]
	v_fmac_f32_e32 v14, v16, v16
	v_fmac_f32_e32 v10, v12, v12
	global_store_dwordx4 v[26:27], v[20:23], off
	v_add_f32_e32 v0, v0, v14
	v_add_f32_e32 v10, v11, v10
	v_add_f32_e32 v0, v0, v10
	v_or_b32_e32 v24, 0x100, v24
	s_waitcnt vmcnt(25)
	v_pk_add_f32 v[2:3], v[2:3], v[208:209]
	s_waitcnt vmcnt(24)
	v_pk_add_f32 v[8:9], v[8:9], v[222:223]
	v_pk_add_f32 v[6:7], v[6:7], v[220:221]
	v_pk_add_f32 v[4:5], v[4:5], v[210:211]
	global_store_dwordx4 v[30:31], v[6:9], off offset:512
	global_store_dwordx4 v[30:31], v[2:5], off offset:528
	v_cvt_pk_bf16_f32 v10, v6, v7
	v_cvt_pk_bf16_f32 v12, v2, v3
	v_mul_f32_e32 v7, v7, v7
	v_mul_f32_e32 v3, v3, v3
	v_fmac_f32_e32 v7, v6, v6
	v_mul_f32_e32 v6, v9, v9
	v_fmac_f32_e32 v3, v2, v2
	v_mul_f32_e32 v2, v5, v5
	v_fmac_f32_e32 v6, v8, v8
	v_fmac_f32_e32 v2, v4, v4
	v_add_f32_e32 v6, v7, v6
	v_add_f32_e32 v2, v3, v2
	v_cvt_pk_bf16_f32 v11, v8, v9
	v_cvt_pk_bf16_f32 v13, v4, v5
	v_lshl_add_u64 v[14:15], s[94:95], 0, v[24:25]
	v_add_f32_e32 v2, v6, v2
	global_store_dwordx4 v[14:15], v[10:13], off
	v_add_f32_e32 v0, v0, v2
	v_mbcnt_lo_u32_b32 v2, -1, 0
	v_mbcnt_hi_u32_b32 v2, -1, v2
	s_nop 0
	v_lshlrev_b32_e32 v2, 2, v2
	v_xor_b32_e32 v2, 64, v2
	ds_bpermute_b32 v2, v2, v0
	s_waitcnt lgkmcnt(0)
	v_add_f32_e32 v0, v0, v2
	v_mbcnt_lo_u32_b32 v2, -1, 0
	v_mbcnt_hi_u32_b32 v2, -1, v2
	s_nop 0
	v_lshlrev_b32_e32 v2, 2, v2
	v_xor_b32_e32 v2, 0x80, v2
	ds_bpermute_b32 v2, v2, v0
	s_and_saveexec_b64 s[34:35], vcc
	s_cbranch_execz .LBB1_1011
	v_lshlrev_b64 v[4:5], 6, v[18:19]
	v_lshl_add_u64 v[4:5], s[96:97], 0, v[4:5]
	v_lshl_add_u64 v[4:5], s[30:31], 2, v[4:5]
	s_lshl_b32 s30, s44, 2
	s_mov_b32 s31, s76
	v_lshl_add_u64 v[4:5], v[4:5], 0, s[30:31]
	s_waitcnt lgkmcnt(0)
	v_add_f32_e32 v0, v0, v2
	global_store_dword v[4:5], v0, off

; DI float shx(float v, int mask) { const int l = lane_id(); return __int_as_float(__builtin_amdgcn_ds_bpermute((l ^ mask) << 2, __float_as_int(v))); }
; DI float rstd16(const float* ssq, int row, int fq) {
;     const f32x4 v = *(const f32x4*)(ssq + (size_t)row * 16 + fq * 4);
;     float s = (v.x + v.y) + (v.z + v.w); s += shx(s, 16); s += shx(s, 32);
;     return __builtin_amdgcn_rsqf(s * (1.0f / 1024.0f) + EPS);
; }
;     DI void operator()(AccRef acc, const Unit& u, int wr, int wc, int fr, int fq) const {
;         float rsv[2][4];
; #pragma unroll
;         for (int ai = 0; ai < 2; ++ai)
; #pragma unroll
;             for (int m = 0; m < 4; ++m) rsv[ai][m] = rstd16(ssq, EROW(u, ai, m), fq);
.LBB1_1340:
	v_mbcnt_lo_u32_b32 v0, -1, 0
	v_mbcnt_hi_u32_b32 v0, -1, v0
	s_lshl_b32 s29, s38, 8
	v_add_u32_e32 v0, s47, v0
	s_add_i32 s29, s29, s54
	v_readlane_b32 s40, v253, 6
	v_and_or_b32 v160, v0, 15, s29
	v_ashrrev_i32_e32 v161, 31, v160
	v_and_b32_e32 v0, 48, v0
	v_or_b32_e32 v156, 16, v160
	v_ashrrev_i32_e32 v157, 31, v156
	v_or_b32_e32 v152, 32, v160
	v_ashrrev_i32_e32 v153, 31, v152
	v_or_b32_e32 v148, 48, v160
	v_ashrrev_i32_e32 v149, 31, v148
	v_add_u32_e32 v144, 0x80, v160
	v_ashrrev_i32_e32 v145, 31, v144
	v_add_u32_e32 v140, 0x90, v160
	v_ashrrev_i32_e32 v141, 31, v140
	v_add_u32_e32 v136, 0xa0, v160
	v_ashrrev_i32_e32 v137, 31, v136
	v_add_u32_e32 v134, 0xb0, v160
	v_ashrrev_i32_e32 v135, 31, v134
	s_lshl_b32 s38, s27, 7
	v_readlane_b32 s41, v253, 7
	s_ashr_i32 s39, s38, 31
	s_lshl_b64 s[38:39], s[38:39], 1
	s_mov_b32 s27, s76
	s_andn2_b64 vcc, exec, s[2:3]
	v_mbcnt_lo_u32_b32 v170, -1, 0
	v_mbcnt_hi_u32_b32 v170, -1, v170
	v_lshlrev_b32_e32 v170, 2, v170
	v_xor_b32_e32 v171, 0x80, v170
	v_xor_b32_e32 v170, 64, v170
	v_lshlrev_b64 v[166:167], 6, v[160:161]
	v_lshl_add_u64 v[166:167], s[96:97], 0, v[166:167]
	v_lshl_add_u64 v[166:167], v[166:167], 0, v[0:1]
	global_load_dwordx4 v[180:183], v[166:167], off
	v_lshlrev_b64 v[168:169], 6, v[156:157]
	v_lshl_add_u64 v[168:169], s[96:97], 0, v[168:169]
	v_lshl_add_u64 v[168:169], v[168:169], 0, v[0:1]
	global_load_dwordx4 v[184:187], v[168:169], off
	v_lshlrev_b64 v[166:167], 6, v[152:153]
	v_lshl_add_u64 v[166:167], s[96:97], 0, v[166:167]
	v_lshl_add_u64 v[166:167], v[166:167], 0, v[0:1]
	global_load_dwordx4 v[188:191], v[166:167], off
	v_lshlrev_b64 v[168:169], 6, v[148:149]
	v_lshl_add_u64 v[168:169], s[96:97], 0, v[168:169]
	v_lshl_add_u64 v[168:169], v[168:169], 0, v[0:1]
	global_load_dwordx4 v[192:195], v[168:169], off
	v_lshlrev_b64 v[166:167], 6, v[144:145]
	v_lshl_add_u64 v[166:167], s[96:97], 0, v[166:167]
	v_lshl_add_u64 v[166:167], v[166:167], 0, v[0:1]
	global_load_dwordx4 v[196:199], v[166:167], off
	v_lshlrev_b64 v[168:169], 6, v[140:141]
	v_lshl_add_u64 v[168:169], s[96:97], 0, v[168:169]
	v_lshl_add_u64 v[168:169], v[168:169], 0, v[0:1]
	global_load_dwordx4 v[200:203], v[168:169], off
	v_lshlrev_b64 v[166:167], 6, v[136:137]
	v_lshl_add_u64 v[166:167], s[96:97], 0, v[166:167]
	v_lshl_add_u64 v[166:167], v[166:167], 0, v[0:1]
	global_load_dwordx4 v[204:207], v[166:167], off
	v_lshlrev_b64 v[168:169], 6, v[134:135]
	v_lshl_add_u64 v[168:169], s[96:97], 0, v[168:169]
	v_lshl_add_u64 v[168:169], v[168:169], 0, v[0:1]
	global_load_dwordx4 v[208:211], v[168:169], off
	s_waitcnt vmcnt(0)
	v_add_f32_e32 v180, v180, v181
	v_add_f32_e32 v182, v182, v183
	v_add_f32_e32 v184, v184, v185
	v_add_f32_e32 v186, v186, v187
	v_add_f32_e32 v188, v188, v189
	v_add_f32_e32 v190, v190, v191
	v_add_f32_e32 v192, v192, v193
	v_add_f32_e32 v194, v194, v195
	v_add_f32_e32 v196, v196, v197
	v_add_f32_e32 v198, v198, v199
	v_add_f32_e32 v200, v200, v201
	v_add_f32_e32 v202, v202, v203
	v_add_f32_e32 v204, v204, v205
	v_add_f32_e32 v206, v206, v207
	v_add_f32_e32 v208, v208, v209
	v_add_f32_e32 v210, v210, v211
	v_add_f32_e32 v180, v180, v182
	v_add_f32_e32 v184, v184, v186
	v_add_f32_e32 v188, v188, v190
	v_add_f32_e32 v192, v192, v194
	v_add_f32_e32 v196, v196, v198
	v_add_f32_e32 v200, v200, v202
	v_add_f32_e32 v204, v204, v206
	v_add_f32_e32 v208, v208, v210
	ds_bpermute_b32 v181, v170, v180
	ds_bpermute_b32 v185, v170, v184
	ds_bpermute_b32 v189, v170, v188
	ds_bpermute_b32 v193, v170, v192
	ds_bpermute_b32 v197, v170, v196
	ds_bpermute_b32 v201, v170, v200
	ds_bpermute_b32 v205, v170, v204
	ds_bpermute_b32 v209, v170, v208
	s_waitcnt lgkmcnt(0)
	v_add_f32_e32 v180, v180, v181
	v_add_f32_e32 v184, v184, v185
	v_add_f32_e32 v188, v188, v189
	v_add_f32_e32 v192, v192, v193
	v_add_f32_e32 v196, v196, v197
	v_add_f32_e32 v200, v200, v201
	v_add_f32_e32 v204, v204, v205
	v_add_f32_e32 v208, v208, v209
	ds_bpermute_b32 v181, v171, v180
	ds_bpermute_b32 v185, v171, v184
	ds_bpermute_b32 v189, v171, v188
	ds_bpermute_b32 v193, v171, v192
	ds_bpermute_b32 v197, v171, v196
	ds_bpermute_b32 v201, v171, v200
	ds_bpermute_b32 v205, v171, v204
	ds_bpermute_b32 v209, v171, v208
	s_waitcnt lgkmcnt(0)
	v_add_f32_e32 v180, v180, v181
	v_add_f32_e32 v184, v184, v185
	v_add_f32_e32 v188, v188, v189
	v_add_f32_e32 v192, v192, v193
	v_add_f32_e32 v196, v196, v197
	v_add_f32_e32 v200, v200, v201
	v_add_f32_e32 v204, v204, v205
	v_add_f32_e32 v208, v208, v209
	v_fmamk_f32 v180, v180, 0x3a800000, v232
	v_fmamk_f32 v184, v184, 0x3a800000, v232
	v_fmamk_f32 v188, v188, 0x3a800000, v232
	v_fmamk_f32 v192, v192, 0x3a800000, v232
	v_fmamk_f32 v196, v196, 0x3a800000, v232
	v_fmamk_f32 v200, v200, 0x3a800000, v232
	v_fmamk_f32 v204, v204, 0x3a800000, v232
	v_fmamk_f32 v208, v208, 0x3a800000, v232
	v_rsq_f32_e32 v162, v180
	v_rsq_f32_e32 v158, v184
	v_rsq_f32_e32 v154, v188
	v_rsq_f32_e32 v150, v192
	v_rsq_f32_e32 v146, v196
	v_rsq_f32_e32 v142, v200
	v_rsq_f32_e32 v138, v204
	v_rsq_f32_e32 v130, v208
	s_nop 0
	v_pk_mul_f32 v[126:127], v[126:127], v[162:163] op_sel_hi:[1,0]
	v_pk_mul_f32 v[122:123], v[122:123], v[162:163] op_sel_hi:[1,0]
	v_pk_mul_f32 v[124:125], v[124:125], v[162:163] op_sel_hi:[1,0]
	v_pk_mul_f32 v[118:119], v[118:119], v[162:163] op_sel_hi:[1,0]
	v_pk_mul_f32 v[114:115], v[114:115], v[162:163] op_sel_hi:[1,0]
	v_pk_mul_f32 v[116:117], v[116:117], v[162:163] op_sel_hi:[1,0]
	v_pk_mul_f32 v[110:111], v[110:111], v[158:159] op_sel_hi:[1,0]
	v_pk_mul_f32 v[106:107], v[106:107], v[158:159] op_sel_hi:[1,0]
	v_pk_mul_f32 v[108:109], v[108:109], v[158:159] op_sel_hi:[1,0]
; #define EFENCE() asm volatile("" ::: "memory")
; DI u32x4 pk8(const f32x4& a, const f32x4& b) { u32x4 w; w.x = cvtpk(a.x, a.y); w.y = cvtpk(a.z, a.w); w.z = cvtpk(b.x, b.y); w.w = cvtpk(b.z, b.w); return w; }
;     DI void operator()(AccRef acc, const Unit& u, int wr, int wc, int fr, int fq) const {
;     ...
; #pragma unroll
;         for (int ai = 0; ai < 2; ++ai)
; #pragma unroll
;             for (int m = 0; m < 4; ++m) { EFENCE();
;                 const int row = EROW(u, ai, m); const float rs = rsv[ai][m];
;                 f32x4 o[2];
; #pragma unroll
;                 for (int n = 0; n < 2; ++n) { const f32x4 g = acc[ai][0][m][n] * rs, v = acc[ai][1][m][n] * rs;
; #pragma unroll
;                     for (int k = 0; k < 4; ++k) o[n][k] = g[k] * __builtin_amdgcn_rcpf(1.0f + __builtin_amdgcn_exp2f(-LOG2E * g[k])) * v[k]; }
;                 *(u32x4*)(hid + (size_t)row * FF + u.pn * 128 + wc * 32 + 8 * fq) = pk8(o[0], o[1]);
	v_pk_mul_f32 v[102:103], v[102:103], v[158:159] op_sel_hi:[1,0]
	v_pk_mul_f32 v[98:99], v[98:99], v[158:159] op_sel_hi:[1,0]
	v_pk_mul_f32 v[100:101], v[100:101], v[158:159] op_sel_hi:[1,0]
	v_pk_mul_f32 v[94:95], v[94:95], v[154:155] op_sel_hi:[1,0]
	v_pk_mul_f32 v[90:91], v[90:91], v[154:155] op_sel_hi:[1,0]
	v_pk_mul_f32 v[92:93], v[92:93], v[154:155] op_sel_hi:[1,0]
	v_pk_mul_f32 v[86:87], v[86:87], v[154:155] op_sel_hi:[1,0]
	v_pk_mul_f32 v[82:83], v[82:83], v[154:155] op_sel_hi:[1,0]
	v_pk_mul_f32 v[84:85], v[84:85], v[154:155] op_sel_hi:[1,0]
	v_pk_mul_f32 v[78:79], v[78:79], v[150:151] op_sel_hi:[1,0]
	v_pk_mul_f32 v[74:75], v[74:75], v[150:151] op_sel_hi:[1,0]
	v_pk_mul_f32 v[76:77], v[76:77], v[150:151] op_sel_hi:[1,0]
	v_pk_mul_f32 v[70:71], v[70:71], v[150:151] op_sel_hi:[1,0]
	v_pk_mul_f32 v[66:67], v[66:67], v[150:151] op_sel_hi:[1,0]
	v_pk_mul_f32 v[68:69], v[68:69], v[150:151] op_sel_hi:[1,0]
	v_pk_mul_f32 v[62:63], v[62:63], v[146:147] op_sel_hi:[1,0]
	v_pk_mul_f32 v[58:59], v[58:59], v[146:147] op_sel_hi:[1,0]
	v_pk_mul_f32 v[60:61], v[60:61], v[146:147] op_sel_hi:[1,0]
	v_pk_mul_f32 v[54:55], v[54:55], v[146:147] op_sel_hi:[1,0]
	v_pk_mul_f32 v[50:51], v[50:51], v[146:147] op_sel_hi:[1,0]
	v_pk_mul_f32 v[52:53], v[52:53], v[146:147] op_sel_hi:[1,0]
	v_pk_mul_f32 v[46:47], v[46:47], v[142:143] op_sel_hi:[1,0]
	v_pk_mul_f32 v[42:43], v[42:43], v[142:143] op_sel_hi:[1,0]
	v_pk_mul_f32 v[44:45], v[44:45], v[142:143] op_sel_hi:[1,0]
	v_pk_mul_f32 v[38:39], v[38:39], v[142:143] op_sel_hi:[1,0]
	v_pk_mul_f32 v[34:35], v[34:35], v[142:143] op_sel_hi:[1,0]
	v_pk_mul_f32 v[36:37], v[36:37], v[142:143] op_sel_hi:[1,0]
	v_pk_mul_f32 v[30:31], v[30:31], v[138:139] op_sel_hi:[1,0]
	v_pk_mul_f32 v[26:27], v[26:27], v[138:139] op_sel_hi:[1,0]
	v_pk_mul_f32 v[28:29], v[28:29], v[138:139] op_sel_hi:[1,0]
	v_pk_mul_f32 v[22:23], v[22:23], v[138:139] op_sel_hi:[1,0]
	v_pk_mul_f32 v[18:19], v[18:19], v[138:139] op_sel_hi:[1,0]
	v_pk_mul_f32 v[20:21], v[20:21], v[138:139] op_sel_hi:[1,0]
	v_mul_f32_e32 v131, 0xbfb8aa3b, v126
	v_exp_f32_e32 v131, v131
	s_nop 0
	v_add_f32_e32 v131, 1.0, v131
	v_rcp_f32_e32 v132, v131
	v_mul_f32_e32 v131, 0xbfb8aa3b, v127
	v_exp_f32_e32 v131, v131
	s_nop 0
	v_add_f32_e32 v131, 1.0, v131
	v_rcp_f32_e32 v133, v131
	v_pk_mul_f32 v[14:15], v[14:15], v[130:131] op_sel_hi:[1,0]
	v_pk_mul_f32 v[10:11], v[10:11], v[130:131] op_sel_hi:[1,0]
	v_pk_mul_f32 v[12:13], v[12:13], v[130:131] op_sel_hi:[1,0]
	v_pk_mul_f32 v[126:127], v[126:127], v[132:133]
	v_pk_mul_f32 v[6:7], v[6:7], v[130:131] op_sel_hi:[1,0]
	v_pk_mul_f32 v[122:123], v[122:123], v[126:127]
	v_pk_mul_f32 v[126:127], v[128:129], v[162:163] op_sel_hi:[1,0]
	v_pk_mul_f32 v[2:3], v[2:3], v[130:131] op_sel_hi:[1,0]
	v_mul_f32_e32 v128, 0xbfb8aa3b, v126
	v_mul_f32_e32 v129, 0xbfb8aa3b, v127
	v_exp_f32_e32 v128, v128
	v_exp_f32_e32 v129, v129
	v_pk_mul_f32 v[4:5], v[4:5], v[130:131] op_sel_hi:[1,0]
	v_add_f32_e32 v128, 1.0, v128
	v_add_f32_e32 v129, 1.0, v129
	v_rcp_f32_e32 v128, v128
	v_rcp_f32_e32 v129, v129
	s_nop 0
	v_pk_mul_f32 v[126:127], v[126:127], v[128:129]
	s_nop 0
	v_pk_mul_f32 v[124:125], v[124:125], v[126:127]
	v_mul_f32_e32 v126, 0xbfb8aa3b, v118
	v_mul_f32_e32 v127, 0xbfb8aa3b, v119
	v_exp_f32_e32 v126, v126
	v_exp_f32_e32 v127, v127
	v_add_f32_e32 v126, 1.0, v126
	v_add_f32_e32 v127, 1.0, v127
	v_rcp_f32_e32 v126, v126
	v_rcp_f32_e32 v127, v127
	s_nop 0
	v_pk_mul_f32 v[118:119], v[118:119], v[126:127]
	s_nop 0
	v_pk_mul_f32 v[114:115], v[114:115], v[118:119]
	v_pk_mul_f32 v[118:119], v[120:121], v[162:163] op_sel_hi:[1,0]
	s_nop 0
	v_mul_f32_e32 v120, 0xbfb8aa3b, v118
	v_mul_f32_e32 v121, 0xbfb8aa3b, v119
	v_exp_f32_e32 v120, v120
	v_exp_f32_e32 v121, v121
	v_add_f32_e32 v120, 1.0, v120
	v_add_f32_e32 v121, 1.0, v121
	v_rcp_f32_e32 v120, v120
	v_rcp_f32_e32 v121, v121
	s_nop 0
	v_pk_mul_f32 v[118:119], v[118:119], v[120:121]
	s_nop 0
	v_pk_mul_f32 v[120:121], v[116:117], v[118:119]
	v_cvt_pk_bf16_f32 v118, v114, v115
	v_mov_b64_e32 v[114:115], s[40:41]
	v_cvt_pk_bf16_f32 v119, v120, v121
	v_mad_i64_i32 v[120:121], s[40:41], v160, s85, v[114:115]
	v_lshl_add_u64 v[120:121], v[120:121], 0, s[38:39]
	v_lshl_add_u64 v[120:121], v[120:121], 0, s[26:27]
	v_cvt_pk_bf16_f32 v116, v122, v123
	v_cvt_pk_bf16_f32 v117, v124, v125
	v_lshl_add_u64 v[120:121], v[120:121], 0, v[0:1]
	global_store_dwordx4 v[120:121], v[116:119], off
	s_nop 1
	v_mul_f32_e32 v116, 0xbfb8aa3b, v110
	v_mul_f32_e32 v117, 0xbfb8aa3b, v111
	v_exp_f32_e32 v116, v116
	v_exp_f32_e32 v117, v117
	v_add_f32_e32 v116, 1.0, v116
	v_add_f32_e32 v117, 1.0, v117
	v_rcp_f32_e32 v116, v116
	v_rcp_f32_e32 v117, v117
	s_nop 0
	v_pk_mul_f32 v[110:111], v[110:111], v[116:117]
	s_nop 0
	v_pk_mul_f32 v[106:107], v[106:107], v[110:111]
	v_pk_mul_f32 v[110:111], v[112:113], v[158:159] op_sel_hi:[1,0]
	s_nop 0
	v_mul_f32_e32 v112, 0xbfb8aa3b, v110
	v_mul_f32_e32 v113, 0xbfb8aa3b, v111
	v_exp_f32_e32 v112, v112
	v_exp_f32_e32 v113, v113
	v_add_f32_e32 v112, 1.0, v112
	v_add_f32_e32 v113, 1.0, v113
	v_rcp_f32_e32 v112, v112
	v_rcp_f32_e32 v113, v113
	s_nop 0
	v_pk_mul_f32 v[110:111], v[110:111], v[112:113]
	s_nop 0
	v_pk_mul_f32 v[108:109], v[108:109], v[110:111]
	v_mul_f32_e32 v110, 0xbfb8aa3b, v102
	v_mul_f32_e32 v111, 0xbfb8aa3b, v103
	v_exp_f32_e32 v110, v110
	v_exp_f32_e32 v111, v111
	v_add_f32_e32 v110, 1.0, v110
	v_add_f32_e32 v111, 1.0, v111
	v_rcp_f32_e32 v110, v110
	v_rcp_f32_e32 v111, v111
	s_nop 0
	v_pk_mul_f32 v[102:103], v[102:103], v[110:111]
	s_nop 0
	v_pk_mul_f32 v[102:103], v[98:99], v[102:103]
	v_pk_mul_f32 v[98:99], v[104:105], v[158:159] op_sel_hi:[1,0]
	s_nop 0
	v_mul_f32_e32 v104, 0xbfb8aa3b, v98
; #define EFENCE() asm volatile("" ::: "memory")
; DI u32x4 pk8(const f32x4& a, const f32x4& b) { u32x4 w; w.x = cvtpk(a.x, a.y); w.y = cvtpk(a.z, a.w); w.z = cvtpk(b.x, b.y); w.w = cvtpk(b.z, b.w); return w; }
;     DI void operator()(AccRef acc, const Unit& u, int wr, int wc, int fr, int fq) const {
;     ...
;             for (int m = 0; m < 4; ++m) { EFENCE();
;                 const int row = EROW(u, ai, m); const float rs = rsv[ai][m];
;                 f32x4 o[2];
; #pragma unroll
;                 for (int n = 0; n < 2; ++n) { const f32x4 g = acc[ai][0][m][n] * rs, v = acc[ai][1][m][n] * rs;
; #pragma unroll
;                     for (int k = 0; k < 4; ++k) o[n][k] = g[k] * __builtin_amdgcn_rcpf(1.0f + __builtin_amdgcn_exp2f(-LOG2E * g[k])) * v[k]; }
;                 *(u32x4*)(hid + (size_t)row * FF + u.pn * 128 + wc * 32 + 8 * fq) = pk8(o[0], o[1]);
	v_mul_f32_e32 v105, 0xbfb8aa3b, v99
	v_exp_f32_e32 v104, v104
	v_exp_f32_e32 v105, v105
	v_add_f32_e32 v104, 1.0, v104
	v_add_f32_e32 v105, 1.0, v105
	v_rcp_f32_e32 v104, v104
	v_rcp_f32_e32 v105, v105
	s_nop 0
	v_pk_mul_f32 v[98:99], v[98:99], v[104:105]
	s_nop 0
	v_pk_mul_f32 v[104:105], v[100:101], v[98:99]
	v_cvt_pk_bf16_f32 v100, v102, v103
	v_mad_i64_i32 v[102:103], s[40:41], v156, s85, v[114:115]
	v_lshl_add_u64 v[102:103], v[102:103], 0, s[38:39]
	v_lshl_add_u64 v[102:103], v[102:103], 0, s[26:27]
	v_cvt_pk_bf16_f32 v98, v106, v107
	v_cvt_pk_bf16_f32 v99, v108, v109
	v_cvt_pk_bf16_f32 v101, v104, v105
	v_lshl_add_u64 v[102:103], v[102:103], 0, v[0:1]
	global_store_dwordx4 v[102:103], v[98:101], off
	s_nop 1
	v_mul_f32_e32 v98, 0xbfb8aa3b, v94
	v_mul_f32_e32 v99, 0xbfb8aa3b, v95
	v_exp_f32_e32 v98, v98
	v_exp_f32_e32 v99, v99
	v_add_f32_e32 v98, 1.0, v98
	v_add_f32_e32 v99, 1.0, v99
	v_rcp_f32_e32 v98, v98
	v_rcp_f32_e32 v99, v99
	s_nop 0
	v_pk_mul_f32 v[94:95], v[94:95], v[98:99]
	s_nop 0
	v_pk_mul_f32 v[90:91], v[90:91], v[94:95]
	v_pk_mul_f32 v[94:95], v[96:97], v[154:155] op_sel_hi:[1,0]
	s_nop 0
	v_mul_f32_e32 v96, 0xbfb8aa3b, v94
	v_mul_f32_e32 v97, 0xbfb8aa3b, v95
	v_exp_f32_e32 v96, v96
	v_exp_f32_e32 v97, v97
	v_add_f32_e32 v96, 1.0, v96
	v_add_f32_e32 v97, 1.0, v97
	v_rcp_f32_e32 v96, v96
	v_rcp_f32_e32 v97, v97
	s_nop 0
	v_pk_mul_f32 v[94:95], v[94:95], v[96:97]
	s_nop 0
	v_pk_mul_f32 v[92:93], v[92:93], v[94:95]
	v_mul_f32_e32 v94, 0xbfb8aa3b, v86
	v_mul_f32_e32 v95, 0xbfb8aa3b, v87
	v_exp_f32_e32 v94, v94
	v_exp_f32_e32 v95, v95
	v_add_f32_e32 v94, 1.0, v94
	v_add_f32_e32 v95, 1.0, v95
	v_rcp_f32_e32 v94, v94
	v_rcp_f32_e32 v95, v95
	s_nop 0
	v_pk_mul_f32 v[86:87], v[86:87], v[94:95]
	s_nop 0
	v_pk_mul_f32 v[86:87], v[82:83], v[86:87]
	v_pk_mul_f32 v[82:83], v[88:89], v[154:155] op_sel_hi:[1,0]
	s_nop 0
	v_mul_f32_e32 v88, 0xbfb8aa3b, v82
	v_mul_f32_e32 v89, 0xbfb8aa3b, v83
	v_exp_f32_e32 v88, v88
	v_exp_f32_e32 v89, v89
	v_add_f32_e32 v88, 1.0, v88
	v_add_f32_e32 v89, 1.0, v89
	v_rcp_f32_e32 v88, v88
	v_rcp_f32_e32 v89, v89
	s_nop 0
	v_pk_mul_f32 v[82:83], v[82:83], v[88:89]
	s_nop 0
	v_pk_mul_f32 v[88:89], v[84:85], v[82:83]
	v_cvt_pk_bf16_f32 v84, v86, v87
	v_mad_i64_i32 v[86:87], s[40:41], v152, s85, v[114:115]
	v_lshl_add_u64 v[86:87], v[86:87], 0, s[38:39]
	v_lshl_add_u64 v[86:87], v[86:87], 0, s[26:27]
	v_cvt_pk_bf16_f32 v82, v90, v91
	v_cvt_pk_bf16_f32 v83, v92, v93
	v_cvt_pk_bf16_f32 v85, v88, v89
	v_lshl_add_u64 v[86:87], v[86:87], 0, v[0:1]
	global_store_dwordx4 v[86:87], v[82:85], off
	s_nop 1
	v_mul_f32_e32 v82, 0xbfb8aa3b, v78
	v_mul_f32_e32 v83, 0xbfb8aa3b, v79
	v_exp_f32_e32 v82, v82
	v_exp_f32_e32 v83, v83
	v_add_f32_e32 v82, 1.0, v82
	v_add_f32_e32 v83, 1.0, v83
	v_rcp_f32_e32 v82, v82
	v_rcp_f32_e32 v83, v83
	s_nop 0
	v_pk_mul_f32 v[78:79], v[78:79], v[82:83]
	s_nop 0
	v_pk_mul_f32 v[74:75], v[74:75], v[78:79]
	v_pk_mul_f32 v[78:79], v[80:81], v[150:151] op_sel_hi:[1,0]
	s_nop 0
	v_mul_f32_e32 v80, 0xbfb8aa3b, v78
	v_mul_f32_e32 v81, 0xbfb8aa3b, v79
	v_exp_f32_e32 v80, v80
	v_exp_f32_e32 v81, v81
	v_add_f32_e32 v80, 1.0, v80
	v_add_f32_e32 v81, 1.0, v81
	v_rcp_f32_e32 v80, v80
	v_rcp_f32_e32 v81, v81
	s_nop 0
	v_pk_mul_f32 v[78:79], v[78:79], v[80:81]
	s_nop 0
	v_pk_mul_f32 v[76:77], v[76:77], v[78:79]
	v_mul_f32_e32 v78, 0xbfb8aa3b, v70
	v_mul_f32_e32 v79, 0xbfb8aa3b, v71
	v_exp_f32_e32 v78, v78
	v_exp_f32_e32 v79, v79
	v_add_f32_e32 v78, 1.0, v78
	v_add_f32_e32 v79, 1.0, v79
	v_rcp_f32_e32 v78, v78
	v_rcp_f32_e32 v79, v79
	s_nop 0
	v_pk_mul_f32 v[70:71], v[70:71], v[78:79]
	s_nop 0
	v_pk_mul_f32 v[70:71], v[66:67], v[70:71]
	v_pk_mul_f32 v[66:67], v[72:73], v[150:151] op_sel_hi:[1,0]
	s_nop 0
	v_mul_f32_e32 v72, 0xbfb8aa3b, v66
	v_mul_f32_e32 v73, 0xbfb8aa3b, v67
	v_exp_f32_e32 v72, v72
	v_exp_f32_e32 v73, v73
	v_add_f32_e32 v72, 1.0, v72
	v_add_f32_e32 v73, 1.0, v73
	v_rcp_f32_e32 v72, v72
	v_rcp_f32_e32 v73, v73
	s_nop 0
	v_pk_mul_f32 v[66:67], v[66:67], v[72:73]
	s_nop 0
	v_pk_mul_f32 v[72:73], v[68:69], v[66:67]
	v_cvt_pk_bf16_f32 v68, v70, v71
	v_mad_i64_i32 v[70:71], s[40:41], v148, s85, v[114:115]
	v_lshl_add_u64 v[70:71], v[70:71], 0, s[38:39]
	v_lshl_add_u64 v[70:71], v[70:71], 0, s[26:27]
	v_cvt_pk_bf16_f32 v66, v74, v75
	v_cvt_pk_bf16_f32 v67, v76, v77
	v_cvt_pk_bf16_f32 v69, v72, v73
	v_lshl_add_u64 v[70:71], v[70:71], 0, v[0:1]
	global_store_dwordx4 v[70:71], v[66:69], off
	s_nop 1
	v_mul_f32_e32 v66, 0xbfb8aa3b, v62
	v_mul_f32_e32 v67, 0xbfb8aa3b, v63
	v_exp_f32_e32 v66, v66
	v_exp_f32_e32 v67, v67
	v_add_f32_e32 v66, 1.0, v66
	v_add_f32_e32 v67, 1.0, v67
	v_rcp_f32_e32 v66, v66
	v_rcp_f32_e32 v67, v67
	s_nop 0
	v_pk_mul_f32 v[62:63], v[62:63], v[66:67]
	s_nop 0
	v_pk_mul_f32 v[58:59], v[58:59], v[62:63]
	v_pk_mul_f32 v[62:63], v[64:65], v[146:147] op_sel_hi:[1,0]
	s_nop 0
	v_mul_f32_e32 v64, 0xbfb8aa3b, v62
	v_mul_f32_e32 v65, 0xbfb8aa3b, v63
	v_exp_f32_e32 v64, v64
	v_exp_f32_e32 v65, v65
	v_add_f32_e32 v64, 1.0, v64
	v_add_f32_e32 v65, 1.0, v65
	v_rcp_f32_e32 v64, v64
	v_rcp_f32_e32 v65, v65
	s_nop 0
	v_pk_mul_f32 v[62:63], v[62:63], v[64:65]
	s_nop 0
	v_pk_mul_f32 v[60:61], v[60:61], v[62:63]
	v_mul_f32_e32 v62, 0xbfb8aa3b, v54
	v_mul_f32_e32 v63, 0xbfb8aa3b, v55
	v_exp_f32_e32 v62, v62
	v_exp_f32_e32 v63, v63
	v_add_f32_e32 v62, 1.0, v62
	v_add_f32_e32 v63, 1.0, v63
	v_rcp_f32_e32 v62, v62
	v_rcp_f32_e32 v63, v63
	s_nop 0
	v_pk_mul_f32 v[54:55], v[54:55], v[62:63]
	s_nop 0
	v_pk_mul_f32 v[54:55], v[50:51], v[54:55]
	v_pk_mul_f32 v[50:51], v[56:57], v[146:147] op_sel_hi:[1,0]
	s_nop 0
	v_mul_f32_e32 v56, 0xbfb8aa3b, v50
	v_mul_f32_e32 v57, 0xbfb8aa3b, v51
	v_exp_f32_e32 v56, v56
; #define GET_TID(wv) int tid_ = (wv) * 64 + lane_id(); asm volatile("" : "+v"(tid_))
; #define PG8_BAR __builtin_amdgcn_s_barrier()
; #define EFENCE() asm volatile("" ::: "memory")
; DI u32x4 pk8(const f32x4& a, const f32x4& b) { u32x4 w; w.x = cvtpk(a.x, a.y); w.y = cvtpk(a.z, a.w); w.z = cvtpk(b.x, b.y); w.w = cvtpk(b.z, b.w); return w; }
; template <class Epi, class Sched>
; __device__ __forceinline__ void gemm_phase(LAS unsigned char* lds, const Gemm g, const Sched& S, const Epi& E, const int wid_in) {
;     ...
;         { GET_TID(wid); const int l_ = tid_ & 63; E(acc, cur, wr, wc, l_ & 15, l_ >> 4); }
;         if (!has_next) break;
;         PG8_IDS();
; #pragma unroll
;         for (int a = 0; a < 2; ++a)
; #pragma unroll
;             for (int b = 0; b < 2; ++b)
; #pragma unroll
;                 for (int m = 0; m < 4; ++m)
; #pragma unroll
;                     for (int n = 0; n < 2; ++n) acc[a][b][m][n] = (f32x4){0.f, 0.f, 0.f, 0.f};
;         cur = nxt; cA = nA; cB = nB; ++ui;
;         if (wr == 1) PG8_BAR;
;     DI void operator()(AccRef acc, const Unit& u, int wr, int wc, int fr, int fq) const {
;     ...
;             for (int m = 0; m < 4; ++m) { EFENCE();
;                 const int row = EROW(u, ai, m); const float rs = rsv[ai][m];
;                 f32x4 o[2];
; #pragma unroll
;                 for (int n = 0; n < 2; ++n) { const f32x4 g = acc[ai][0][m][n] * rs, v = acc[ai][1][m][n] * rs;
; #pragma unroll
;                     for (int k = 0; k < 4; ++k) o[n][k] = g[k] * __builtin_amdgcn_rcpf(1.0f + __builtin_amdgcn_exp2f(-LOG2E * g[k])) * v[k]; }
;                 *(u32x4*)(hid + (size_t)row * FF + u.pn * 128 + wc * 32 + 8 * fq) = pk8(o[0], o[1]);
	v_exp_f32_e32 v57, v57
	v_add_f32_e32 v56, 1.0, v56
	v_add_f32_e32 v57, 1.0, v57
	v_rcp_f32_e32 v56, v56
	v_rcp_f32_e32 v57, v57
	s_nop 0
	v_pk_mul_f32 v[50:51], v[50:51], v[56:57]
	s_nop 0
	v_pk_mul_f32 v[56:57], v[52:53], v[50:51]
	v_cvt_pk_bf16_f32 v52, v54, v55
	v_mad_i64_i32 v[54:55], s[40:41], v144, s85, v[114:115]
	v_lshl_add_u64 v[54:55], v[54:55], 0, s[38:39]
	v_lshl_add_u64 v[54:55], v[54:55], 0, s[26:27]
	v_cvt_pk_bf16_f32 v50, v58, v59
	v_cvt_pk_bf16_f32 v51, v60, v61
	v_cvt_pk_bf16_f32 v53, v56, v57
	v_lshl_add_u64 v[54:55], v[54:55], 0, v[0:1]
	global_store_dwordx4 v[54:55], v[50:53], off
	s_nop 1
	v_mul_f32_e32 v50, 0xbfb8aa3b, v46
	v_mul_f32_e32 v51, 0xbfb8aa3b, v47
	v_exp_f32_e32 v50, v50
	v_exp_f32_e32 v51, v51
	v_add_f32_e32 v50, 1.0, v50
	v_add_f32_e32 v51, 1.0, v51
	v_rcp_f32_e32 v50, v50
	v_rcp_f32_e32 v51, v51
	s_nop 0
	v_pk_mul_f32 v[46:47], v[46:47], v[50:51]
	s_nop 0
	v_pk_mul_f32 v[42:43], v[42:43], v[46:47]
	v_pk_mul_f32 v[46:47], v[48:49], v[142:143] op_sel_hi:[1,0]
	s_nop 0
	v_mul_f32_e32 v48, 0xbfb8aa3b, v46
	v_mul_f32_e32 v49, 0xbfb8aa3b, v47
	v_exp_f32_e32 v48, v48
	v_exp_f32_e32 v49, v49
	v_add_f32_e32 v48, 1.0, v48
	v_add_f32_e32 v49, 1.0, v49
	v_rcp_f32_e32 v48, v48
	v_rcp_f32_e32 v49, v49
	s_nop 0
	v_pk_mul_f32 v[46:47], v[46:47], v[48:49]
	s_nop 0
	v_pk_mul_f32 v[44:45], v[44:45], v[46:47]
	v_mul_f32_e32 v46, 0xbfb8aa3b, v38
	v_mul_f32_e32 v47, 0xbfb8aa3b, v39
	v_exp_f32_e32 v46, v46
	v_exp_f32_e32 v47, v47
	v_add_f32_e32 v46, 1.0, v46
	v_add_f32_e32 v47, 1.0, v47
	v_rcp_f32_e32 v46, v46
	v_rcp_f32_e32 v47, v47
	s_nop 0
	v_pk_mul_f32 v[38:39], v[38:39], v[46:47]
	s_nop 0
	v_pk_mul_f32 v[38:39], v[34:35], v[38:39]
	v_pk_mul_f32 v[34:35], v[40:41], v[142:143] op_sel_hi:[1,0]
	s_nop 0
	v_mul_f32_e32 v40, 0xbfb8aa3b, v34
	v_mul_f32_e32 v41, 0xbfb8aa3b, v35
	v_exp_f32_e32 v40, v40
	v_exp_f32_e32 v41, v41
	v_add_f32_e32 v40, 1.0, v40
	v_add_f32_e32 v41, 1.0, v41
	v_rcp_f32_e32 v40, v40
	v_rcp_f32_e32 v41, v41
	s_nop 0
	v_pk_mul_f32 v[34:35], v[34:35], v[40:41]
	s_nop 0
	v_pk_mul_f32 v[40:41], v[36:37], v[34:35]
	v_cvt_pk_bf16_f32 v36, v38, v39
	v_mad_i64_i32 v[38:39], s[40:41], v140, s85, v[114:115]
	v_lshl_add_u64 v[38:39], v[38:39], 0, s[38:39]
	v_lshl_add_u64 v[38:39], v[38:39], 0, s[26:27]
	v_cvt_pk_bf16_f32 v34, v42, v43
	v_cvt_pk_bf16_f32 v35, v44, v45
	v_cvt_pk_bf16_f32 v37, v40, v41
	v_lshl_add_u64 v[38:39], v[38:39], 0, v[0:1]
	global_store_dwordx4 v[38:39], v[34:37], off
	s_nop 1
	v_mul_f32_e32 v34, 0xbfb8aa3b, v30
	v_mul_f32_e32 v35, 0xbfb8aa3b, v31
	v_exp_f32_e32 v34, v34
	v_exp_f32_e32 v35, v35
	v_add_f32_e32 v34, 1.0, v34
	v_add_f32_e32 v35, 1.0, v35
	v_rcp_f32_e32 v34, v34
	v_rcp_f32_e32 v35, v35
	s_nop 0
	v_pk_mul_f32 v[30:31], v[30:31], v[34:35]
	s_nop 0
	v_pk_mul_f32 v[26:27], v[26:27], v[30:31]
	v_pk_mul_f32 v[30:31], v[32:33], v[138:139] op_sel_hi:[1,0]
	s_nop 0
	v_mul_f32_e32 v32, 0xbfb8aa3b, v30
	v_mul_f32_e32 v33, 0xbfb8aa3b, v31
	v_exp_f32_e32 v32, v32
	v_exp_f32_e32 v33, v33
	v_add_f32_e32 v32, 1.0, v32
	v_add_f32_e32 v33, 1.0, v33
	v_rcp_f32_e32 v32, v32
	v_rcp_f32_e32 v33, v33
	s_nop 0
	v_pk_mul_f32 v[30:31], v[30:31], v[32:33]
	s_nop 0
	v_pk_mul_f32 v[28:29], v[28:29], v[30:31]
	v_mul_f32_e32 v30, 0xbfb8aa3b, v22
	v_mul_f32_e32 v31, 0xbfb8aa3b, v23
	v_exp_f32_e32 v30, v30
	v_exp_f32_e32 v31, v31
	v_add_f32_e32 v30, 1.0, v30
	v_add_f32_e32 v31, 1.0, v31
	v_rcp_f32_e32 v30, v30
	v_rcp_f32_e32 v31, v31
	s_nop 0
	v_pk_mul_f32 v[22:23], v[22:23], v[30:31]
	s_nop 0
	v_pk_mul_f32 v[22:23], v[18:19], v[22:23]
	v_pk_mul_f32 v[18:19], v[24:25], v[138:139] op_sel_hi:[1,0]
	s_nop 0
	v_mul_f32_e32 v24, 0xbfb8aa3b, v18
	v_mul_f32_e32 v25, 0xbfb8aa3b, v19
	v_exp_f32_e32 v24, v24
	v_exp_f32_e32 v25, v25
	v_add_f32_e32 v24, 1.0, v24
	v_add_f32_e32 v25, 1.0, v25
	v_rcp_f32_e32 v24, v24
	v_rcp_f32_e32 v25, v25
	s_nop 0
	v_pk_mul_f32 v[18:19], v[18:19], v[24:25]
	s_nop 0
	v_pk_mul_f32 v[24:25], v[20:21], v[18:19]
	v_cvt_pk_bf16_f32 v20, v22, v23
	v_mad_i64_i32 v[22:23], s[40:41], v136, s85, v[114:115]
	v_lshl_add_u64 v[22:23], v[22:23], 0, s[38:39]
	v_lshl_add_u64 v[22:23], v[22:23], 0, s[26:27]
	v_cvt_pk_bf16_f32 v18, v26, v27
	v_cvt_pk_bf16_f32 v19, v28, v29
	v_cvt_pk_bf16_f32 v21, v24, v25
	v_lshl_add_u64 v[22:23], v[22:23], 0, v[0:1]
	global_store_dwordx4 v[22:23], v[18:21], off
	s_nop 1
	v_mul_f32_e32 v18, 0xbfb8aa3b, v14
	v_mul_f32_e32 v19, 0xbfb8aa3b, v15
	v_exp_f32_e32 v18, v18
	v_exp_f32_e32 v19, v19
	v_add_f32_e32 v18, 1.0, v18
	v_add_f32_e32 v19, 1.0, v19
	v_rcp_f32_e32 v18, v18
	v_rcp_f32_e32 v19, v19
	s_nop 0
	v_pk_mul_f32 v[14:15], v[14:15], v[18:19]
	s_nop 0
	v_pk_mul_f32 v[10:11], v[10:11], v[14:15]
	v_pk_mul_f32 v[14:15], v[16:17], v[130:131] op_sel_hi:[1,0]
	s_nop 0
	v_mul_f32_e32 v16, 0xbfb8aa3b, v14
	v_mul_f32_e32 v17, 0xbfb8aa3b, v15
	v_exp_f32_e32 v16, v16
	v_exp_f32_e32 v17, v17
	v_add_f32_e32 v16, 1.0, v16
	v_add_f32_e32 v17, 1.0, v17
	v_rcp_f32_e32 v16, v16
	v_rcp_f32_e32 v17, v17
	s_nop 0
	v_pk_mul_f32 v[14:15], v[14:15], v[16:17]
	s_nop 0
	v_pk_mul_f32 v[12:13], v[12:13], v[14:15]
	v_mul_f32_e32 v14, 0xbfb8aa3b, v6
	v_mul_f32_e32 v15, 0xbfb8aa3b, v7
	v_exp_f32_e32 v14, v14
	v_exp_f32_e32 v15, v15
	v_add_f32_e32 v14, 1.0, v14
	v_add_f32_e32 v15, 1.0, v15
	v_rcp_f32_e32 v14, v14
	v_rcp_f32_e32 v15, v15
	s_nop 0
	v_pk_mul_f32 v[6:7], v[6:7], v[14:15]
	s_nop 0
	v_pk_mul_f32 v[6:7], v[2:3], v[6:7]
	v_pk_mul_f32 v[2:3], v[8:9], v[130:131] op_sel_hi:[1,0]
	s_nop 0
	v_mul_f32_e32 v8, 0xbfb8aa3b, v2
	v_mul_f32_e32 v9, 0xbfb8aa3b, v3
	v_exp_f32_e32 v8, v8
	v_exp_f32_e32 v9, v9
	v_add_f32_e32 v8, 1.0, v8
	v_add_f32_e32 v9, 1.0, v9
	v_rcp_f32_e32 v8, v8
	v_rcp_f32_e32 v9, v9
	s_nop 0
	v_pk_mul_f32 v[2:3], v[2:3], v[8:9]
	s_nop 0
	v_pk_mul_f32 v[8:9], v[4:5], v[2:3]
	v_cvt_pk_bf16_f32 v4, v6, v7
	v_mad_i64_i32 v[6:7], s[40:41], v134, s85, v[114:115]
	v_lshl_add_u64 v[6:7], v[6:7], 0, s[38:39]
	v_lshl_add_u64 v[6:7], v[6:7], 0, s[26:27]
	v_cvt_pk_bf16_f32 v2, v10, v11
	v_cvt_pk_bf16_f32 v3, v12, v13
	v_cvt_pk_bf16_f32 v5, v8, v9
	v_lshl_add_u64 v[6:7], v[6:7], 0, v[0:1]
	s_mov_b64 s[38:39], -1
	global_store_dwordx4 v[6:7], v[2:5], off
	s_cbranch_vccnz .LBB1_1333
	v_mbcnt_lo_u32_b32 v0, -1, 0
	v_mbcnt_hi_u32_b32 v0, -1, v0
	s_andn2_b64 vcc, exec, s[12:13]
	v_add_u32_e32 v2, s47, v0
	s_cbranch_vccnz .LBB1_1332
	s_barrier
	s_branch .LBB1_1332

; #define EFENCE() asm volatile("" ::: "memory")
; DI float sum4q(float s) { s += shx(s, 16); s += shx(s, 32); return s; }
; DI float sq4(const f32x4& v) { return (v.x * v.x + v.y * v.y) + (v.z * v.z + v.w * v.w); }
; DI u32x4 pk8(const f32x4& a, const f32x4& b) { u32x4 w; w.x = cvtpk(a.x, a.y); w.y = cvtpk(a.z, a.w); w.z = cvtpk(b.x, b.y); w.w = cvtpk(b.z, b.w); return w; }
;     DI void operator()(AccRef acc, const Unit& u, int wr, int wc, int fr, int fq) const {
;     ...
;             for (int m = 0; m < 4; ++m) { if ((m & 1) == 0) EFENCE();
;                 const int row = EROW(u, ai, m); float ss = 0.f;
; #pragma unroll
;                 for (int bj = 0; bj < 2; ++bj) {
;                     const size_t off = (size_t)row * DM + u.pn * 256 + bj * 128 + wc * 32 + 8 * fq;
;                     f32x4 x0 = *(const f32x4*)(xin + off), x1 = *(const f32x4*)(xin + off + 4);
;                     x0 += acc[ai][bj][m][0] * alpha; x1 += acc[ai][bj][m][1] * alpha;
;                     *(f32x4*)(xout + off) = x0; *(f32x4*)(xout + off + 4) = x1;
;                     *(u32x4*)(xb + off) = pk8(x0, x1); ss += sq4(x0) + sq4(x1);
;                 }
;                 ss = sum4q(ss);
;                 if (fq == 0) ssq[(size_t)row * 16 + u.pn * 4 + wc] = ss;
.LBB1_1396:
	v_mbcnt_lo_u32_b32 v0, -1, 0
	v_mbcnt_hi_u32_b32 v0, -1, v0
	s_lshl_b32 s36, s61, 8
	v_add_u32_e32 v0, s42, v0
	s_add_i32 s36, s36, s50
	s_nop 0
	v_and_or_b32 v130, v0, 15, s36
	s_lshl_b32 s36, s60, 8
	s_ashr_i32 s37, s36, 31
	v_bfe_u32 v131, v0, 4, 2
	s_or_b64 s[36:37], s[36:37], s[28:29]
	v_lshl_or_b32 v132, v131, 3, s36
	v_cmp_eq_u32_e32 vcc, 0, v131
	v_ashrrev_i32_e32 v131, 31, v130
	v_mov_b32_e32 v133, s37
	v_lshlrev_b64 v[134:135], 10, v[130:131]
	v_lshl_add_u64 v[142:143], v[132:133], 0, v[134:135]
	v_lshlrev_b64 v[144:145], 2, v[142:143]
	v_lshl_add_u64 v[146:147], s[8:9], 0, v[144:145]
	v_lshlrev_b32_e32 v240, 2, v142
	global_load_dwordx4 v[148:151], v240, s[8:9] offset:16
	global_load_dwordx4 v[152:155], v240, s[8:9] offset:0
	global_load_dwordx4 v[156:159], v240, s[8:9] offset:528
	global_load_dwordx4 v[160:163], v240, s[8:9] offset:512
	v_add_u32_e32 v242, 0x10000, v240
	global_load_dwordx4 v[164:167], v242, s[8:9] offset:16
	global_load_dwordx4 v[168:171], v242, s[8:9] offset:0
	global_load_dwordx4 v[172:175], v242, s[8:9] offset:528
	global_load_dwordx4 v[180:183], v242, s[8:9] offset:512
	v_add_u32_e32 v243, 0x20000, v240
	global_load_dwordx4 v[184:187], v243, s[8:9] offset:16
	global_load_dwordx4 v[188:191], v243, s[8:9] offset:0
	global_load_dwordx4 v[192:195], v243, s[8:9] offset:528
	global_load_dwordx4 v[196:199], v243, s[8:9] offset:512
	v_add_u32_e32 v241, 0x30000, v240
	global_load_dwordx4 v[200:203], v241, s[8:9] offset:16
	global_load_dwordx4 v[204:207], v241, s[8:9] offset:0
	global_load_dwordx4 v[208:211], v241, s[8:9] offset:528
	global_load_dwordx4 v[220:223], v241, s[8:9] offset:512
	s_lshl_b32 s36, s60, 2
	s_ashr_i32 s37, s36, 31
	s_waitcnt vmcnt(15)
	v_pk_fma_f32 v[122:123], v[122:123], 0.5, v[148:149] op_sel_hi:[1,0,1]
	s_waitcnt vmcnt(14)
	v_pk_fma_f32 v[128:129], v[128:129], 0.5, v[154:155] op_sel_hi:[1,0,1]
	v_pk_fma_f32 v[126:127], v[126:127], 0.5, v[152:153] op_sel_hi:[1,0,1]
	v_lshl_add_u64 v[138:139], s[16:17], 0, v[144:145]
	v_pk_fma_f32 v[124:125], v[124:125], 0.5, v[150:151] op_sel_hi:[1,0,1]
	global_store_dwordx4 v[138:139], v[126:129], off
	global_store_dwordx4 v[138:139], v[122:125], off offset:16
	v_cvt_pk_bf16_f32 v136, v122, v123
	v_mul_f32_e32 v0, v127, v127
	v_mul_f32_e32 v123, v123, v123
	v_cvt_pk_bf16_f32 v134, v126, v127
	v_lshlrev_b64 v[140:141], 1, v[142:143]
	v_fmac_f32_e32 v0, v126, v126
	v_mul_f32_e32 v126, v129, v129
	v_fmac_f32_e32 v123, v122, v122
	v_mul_f32_e32 v122, v125, v125
	v_cvt_pk_bf16_f32 v135, v128, v129
	v_cvt_pk_bf16_f32 v137, v124, v125
	v_lshl_add_u64 v[142:143], s[94:95], 0, v[140:141]
	v_fmac_f32_e32 v126, v128, v128
	v_fmac_f32_e32 v122, v124, v124
	global_store_dwordx4 v[142:143], v[134:137], off
	v_add_f32_e32 v0, v0, v126
	v_add_f32_e32 v122, v123, v122
	v_add_f32_e32 v0, v0, v122
	v_or_b32_e32 v140, 0x100, v140
	s_waitcnt vmcnt(16)
	v_pk_fma_f32 v[114:115], v[114:115], 0.5, v[156:157] op_sel_hi:[1,0,1]
	s_waitcnt vmcnt(15)
	v_pk_fma_f32 v[120:121], v[120:121], 0.5, v[162:163] op_sel_hi:[1,0,1]
	v_pk_fma_f32 v[118:119], v[118:119], 0.5, v[160:161] op_sel_hi:[1,0,1]
	v_pk_fma_f32 v[116:117], v[116:117], 0.5, v[158:159] op_sel_hi:[1,0,1]
	v_add_u32_e32 v242, 0x80000, v240
	global_load_dwordx4 v[148:151], v242, s[8:9] offset:16
	global_load_dwordx4 v[152:155], v242, s[8:9] offset:0
	global_load_dwordx4 v[156:159], v242, s[8:9] offset:528
	global_load_dwordx4 v[160:163], v242, s[8:9] offset:512
	global_store_dwordx4 v[138:139], v[118:121], off offset:512
	global_store_dwordx4 v[138:139], v[114:117], off offset:528
	v_cvt_pk_bf16_f32 v122, v118, v119
	v_cvt_pk_bf16_f32 v124, v114, v115
	v_mul_f32_e32 v119, v119, v119
	v_mul_f32_e32 v115, v115, v115
	v_fmac_f32_e32 v119, v118, v118
	v_mul_f32_e32 v118, v121, v121
	v_fmac_f32_e32 v115, v114, v114
	v_mul_f32_e32 v114, v117, v117
	v_fmac_f32_e32 v118, v120, v120
	v_fmac_f32_e32 v114, v116, v116
	v_add_f32_e32 v118, v119, v118
	v_add_f32_e32 v114, v115, v114
	v_cvt_pk_bf16_f32 v123, v120, v121
	v_cvt_pk_bf16_f32 v125, v116, v117
	v_lshl_add_u64 v[126:127], s[94:95], 0, v[140:141]
	v_add_f32_e32 v114, v118, v114
	global_store_dwordx4 v[126:127], v[122:125], off
	v_add_f32_e32 v0, v0, v114
	v_mbcnt_lo_u32_b32 v114, -1, 0
	v_mbcnt_hi_u32_b32 v114, -1, v114
	s_nop 0
	v_lshlrev_b32_e32 v114, 2, v114
	v_xor_b32_e32 v114, 64, v114
	ds_bpermute_b32 v114, v114, v0
	s_waitcnt lgkmcnt(0)
	v_add_f32_e32 v0, v0, v114
	v_mbcnt_lo_u32_b32 v114, -1, 0
	v_mbcnt_hi_u32_b32 v114, -1, v114
	s_nop 0
	v_lshlrev_b32_e32 v114, 2, v114
	v_xor_b32_e32 v114, 0x80, v114
	ds_bpermute_b32 v114, v114, v0
	s_and_saveexec_b64 s[38:39], vcc
	s_cbranch_execz .LBB1_1398
	v_lshlrev_b64 v[116:117], 6, v[130:131]
	v_lshl_add_u64 v[116:117], s[96:97], 0, v[116:117]
	v_lshl_add_u64 v[116:117], s[36:37], 2, v[116:117]
	s_lshl_b32 s40, s49, 2
	s_mov_b32 s41, s76
	v_lshl_add_u64 v[116:117], v[116:117], 0, s[40:41]
	s_waitcnt lgkmcnt(0)
	v_add_f32_e32 v0, v0, v114
	global_store_dword v[116:117], v0, off
; #define EFENCE() asm volatile("" ::: "memory")
; DI float sum4q(float s) { s += shx(s, 16); s += shx(s, 32); return s; }
; DI float sq4(const f32x4& v) { return (v.x * v.x + v.y * v.y) + (v.z * v.z + v.w * v.w); }
; DI u32x4 pk8(const f32x4& a, const f32x4& b) { u32x4 w; w.x = cvtpk(a.x, a.y); w.y = cvtpk(a.z, a.w); w.z = cvtpk(b.x, b.y); w.w = cvtpk(b.z, b.w); return w; }
;     DI void operator()(AccRef acc, const Unit& u, int wr, int wc, int fr, int fq) const {
; #pragma unroll
;         for (int ai = 0; ai < 2; ++ai)
; #pragma unroll
;             for (int m = 0; m < 4; ++m) { if ((m & 1) == 0) EFENCE();
;                 const int row = EROW(u, ai, m); float ss = 0.f;
; #pragma unroll
;                 for (int bj = 0; bj < 2; ++bj) {
;                     const size_t off = (size_t)row * DM + u.pn * 256 + bj * 128 + wc * 32 + 8 * fq;
;                     f32x4 x0 = *(const f32x4*)(xin + off), x1 = *(const f32x4*)(xin + off + 4);
;                     x0 += acc[ai][bj][m][0] * alpha; x1 += acc[ai][bj][m][1] * alpha;
;                     *(f32x4*)(xout + off) = x0; *(f32x4*)(xout + off + 4) = x1;
;                     *(u32x4*)(xb + off) = pk8(x0, x1); ss += sq4(x0) + sq4(x1);
;                 }
;                 ss = sum4q(ss);
;                 if (fq == 0) ssq[(size_t)row * 16 + u.pn * 4 + wc] = ss;
.LBB1_1398:
	s_or_b64 exec, exec, s[38:39]
	s_waitcnt lgkmcnt(0)
	v_or_b32_e32 v114, 16, v130
	v_ashrrev_i32_e32 v115, 31, v114
	v_lshlrev_b64 v[116:117], 10, v[114:115]
	v_lshl_add_u64 v[124:125], v[116:117], 0, v[132:133]
	v_lshlrev_b64 v[126:127], 2, v[124:125]
	v_lshl_add_u64 v[128:129], s[8:9], 0, v[126:127]
	s_waitcnt vmcnt(21)
	v_pk_fma_f32 v[106:107], v[106:107], 0.5, v[164:165] op_sel_hi:[1,0,1]
	s_waitcnt vmcnt(20)
	v_pk_fma_f32 v[112:113], v[112:113], 0.5, v[170:171] op_sel_hi:[1,0,1]
	v_pk_fma_f32 v[110:111], v[110:111], 0.5, v[168:169] op_sel_hi:[1,0,1]
	v_lshl_add_u64 v[120:121], s[16:17], 0, v[126:127]
	v_pk_fma_f32 v[108:109], v[108:109], 0.5, v[166:167] op_sel_hi:[1,0,1]
	global_store_dwordx4 v[120:121], v[110:113], off
	global_store_dwordx4 v[120:121], v[106:109], off offset:16
	v_cvt_pk_bf16_f32 v118, v106, v107
	v_mul_f32_e32 v0, v111, v111
	v_mul_f32_e32 v107, v107, v107
	v_cvt_pk_bf16_f32 v116, v110, v111
	v_lshlrev_b64 v[122:123], 1, v[124:125]
	v_fmac_f32_e32 v0, v110, v110
	v_mul_f32_e32 v110, v113, v113
	v_fmac_f32_e32 v107, v106, v106
	v_mul_f32_e32 v106, v109, v109
	v_cvt_pk_bf16_f32 v117, v112, v113
	v_cvt_pk_bf16_f32 v119, v108, v109
	v_lshl_add_u64 v[124:125], s[94:95], 0, v[122:123]
	v_fmac_f32_e32 v110, v112, v112
	v_fmac_f32_e32 v106, v108, v108
	global_store_dwordx4 v[124:125], v[116:119], off
	v_add_f32_e32 v0, v0, v110
	v_add_f32_e32 v106, v107, v106
	v_add_f32_e32 v0, v0, v106
	v_or_b32_e32 v122, 0x100, v122
	s_waitcnt vmcnt(22)
	v_pk_fma_f32 v[98:99], v[98:99], 0.5, v[172:173] op_sel_hi:[1,0,1]
	s_waitcnt vmcnt(21)
	v_pk_fma_f32 v[104:105], v[104:105], 0.5, v[182:183] op_sel_hi:[1,0,1]
	v_pk_fma_f32 v[102:103], v[102:103], 0.5, v[180:181] op_sel_hi:[1,0,1]
	v_pk_fma_f32 v[100:101], v[100:101], 0.5, v[174:175] op_sel_hi:[1,0,1]
	v_add_u32_e32 v243, 0x90000, v240
	global_load_dwordx4 v[164:167], v243, s[8:9] offset:16
	global_load_dwordx4 v[168:171], v243, s[8:9] offset:0
	global_load_dwordx4 v[172:175], v243, s[8:9] offset:528
	global_load_dwordx4 v[180:183], v243, s[8:9] offset:512
	global_store_dwordx4 v[120:121], v[102:105], off offset:512
	global_store_dwordx4 v[120:121], v[98:101], off offset:528
	v_cvt_pk_bf16_f32 v106, v102, v103
	v_cvt_pk_bf16_f32 v108, v98, v99
	v_mul_f32_e32 v103, v103, v103
	v_mul_f32_e32 v99, v99, v99
	v_fmac_f32_e32 v103, v102, v102
	v_mul_f32_e32 v102, v105, v105
	v_fmac_f32_e32 v99, v98, v98
	v_mul_f32_e32 v98, v101, v101
	v_fmac_f32_e32 v102, v104, v104
	v_fmac_f32_e32 v98, v100, v100
	v_add_f32_e32 v102, v103, v102
	v_add_f32_e32 v98, v99, v98
	v_cvt_pk_bf16_f32 v107, v104, v105
	v_cvt_pk_bf16_f32 v109, v100, v101
	v_lshl_add_u64 v[110:111], s[94:95], 0, v[122:123]
	v_add_f32_e32 v98, v102, v98
	global_store_dwordx4 v[110:111], v[106:109], off
	v_add_f32_e32 v0, v0, v98
	v_mbcnt_lo_u32_b32 v98, -1, 0
	v_mbcnt_hi_u32_b32 v98, -1, v98
	s_nop 0
	v_lshlrev_b32_e32 v98, 2, v98
	v_xor_b32_e32 v98, 64, v98
	ds_bpermute_b32 v98, v98, v0
	s_waitcnt lgkmcnt(0)
	v_add_f32_e32 v0, v0, v98
	v_mbcnt_lo_u32_b32 v98, -1, 0
	v_mbcnt_hi_u32_b32 v98, -1, v98
	s_nop 0
	v_lshlrev_b32_e32 v98, 2, v98
	v_xor_b32_e32 v98, 0x80, v98
	ds_bpermute_b32 v98, v98, v0
	s_and_saveexec_b64 s[38:39], vcc
	s_cbranch_execz .LBB1_1400
	v_lshlrev_b64 v[100:101], 6, v[114:115]
	v_lshl_add_u64 v[100:101], s[96:97], 0, v[100:101]
	v_lshl_add_u64 v[100:101], s[36:37], 2, v[100:101]
	s_lshl_b32 s40, s49, 2
	s_mov_b32 s41, s76
	v_lshl_add_u64 v[100:101], v[100:101], 0, s[40:41]
	s_waitcnt lgkmcnt(0)
	v_add_f32_e32 v0, v0, v98
	global_store_dword v[100:101], v0, off
.LBB1_1400:
	s_or_b64 exec, exec, s[38:39]
	s_waitcnt lgkmcnt(0)
	v_or_b32_e32 v98, 32, v130
	v_ashrrev_i32_e32 v99, 31, v98
	v_lshlrev_b64 v[100:101], 10, v[98:99]
	v_lshl_add_u64 v[108:109], v[100:101], 0, v[132:133]
	v_lshlrev_b64 v[110:111], 2, v[108:109]
	v_lshl_add_u64 v[112:113], s[8:9], 0, v[110:111]
	s_waitcnt vmcnt(27)
	v_pk_fma_f32 v[90:91], v[90:91], 0.5, v[184:185] op_sel_hi:[1,0,1]
	s_waitcnt vmcnt(26)
	v_pk_fma_f32 v[96:97], v[96:97], 0.5, v[190:191] op_sel_hi:[1,0,1]
	v_pk_fma_f32 v[94:95], v[94:95], 0.5, v[188:189] op_sel_hi:[1,0,1]
	v_lshl_add_u64 v[104:105], s[16:17], 0, v[110:111]
	v_pk_fma_f32 v[92:93], v[92:93], 0.5, v[186:187] op_sel_hi:[1,0,1]
	global_store_dwordx4 v[104:105], v[94:97], off
	global_store_dwordx4 v[104:105], v[90:93], off offset:16
	v_cvt_pk_bf16_f32 v102, v90, v91
	v_mul_f32_e32 v0, v95, v95
	v_mul_f32_e32 v91, v91, v91
	v_cvt_pk_bf16_f32 v100, v94, v95
	v_lshlrev_b64 v[106:107], 1, v[108:109]
	v_fmac_f32_e32 v0, v94, v94
	v_mul_f32_e32 v94, v97, v97
	v_fmac_f32_e32 v91, v90, v90
	v_mul_f32_e32 v90, v93, v93
	v_cvt_pk_bf16_f32 v101, v96, v97
	v_cvt_pk_bf16_f32 v103, v92, v93
	v_lshl_add_u64 v[108:109], s[94:95], 0, v[106:107]
	v_fmac_f32_e32 v94, v96, v96
	v_fmac_f32_e32 v90, v92, v92
	global_store_dwordx4 v[108:109], v[100:103], off
	v_add_f32_e32 v0, v0, v94
	v_add_f32_e32 v90, v91, v90
	v_add_f32_e32 v0, v0, v90
	v_or_b32_e32 v106, 0x100, v106
	s_waitcnt vmcnt(28)
	v_pk_fma_f32 v[82:83], v[82:83], 0.5, v[192:193] op_sel_hi:[1,0,1]
	s_waitcnt vmcnt(27)
	v_pk_fma_f32 v[88:89], v[88:89], 0.5, v[198:199] op_sel_hi:[1,0,1]
	v_pk_fma_f32 v[86:87], v[86:87], 0.5, v[196:197] op_sel_hi:[1,0,1]
	v_pk_fma_f32 v[84:85], v[84:85], 0.5, v[194:195] op_sel_hi:[1,0,1]
	v_add_u32_e32 v241, 0xa0000, v240
	global_load_dwordx4 v[184:187], v241, s[8:9] offset:16
	global_load_dwordx4 v[188:191], v241, s[8:9] offset:0
	global_load_dwordx4 v[192:195], v241, s[8:9] offset:528
	global_load_dwordx4 v[196:199], v241, s[8:9] offset:512
	global_store_dwordx4 v[104:105], v[86:89], off offset:512
	global_store_dwordx4 v[104:105], v[82:85], off offset:528
	v_cvt_pk_bf16_f32 v90, v86, v87
	v_cvt_pk_bf16_f32 v92, v82, v83
	v_mul_f32_e32 v87, v87, v87
	v_mul_f32_e32 v83, v83, v83
	v_fmac_f32_e32 v87, v86, v86
	v_mul_f32_e32 v86, v89, v89
	v_fmac_f32_e32 v83, v82, v82
	v_mul_f32_e32 v82, v85, v85
	v_fmac_f32_e32 v86, v88, v88
	v_fmac_f32_e32 v82, v84, v84
	v_add_f32_e32 v86, v87, v86
	v_add_f32_e32 v82, v83, v82
	v_cvt_pk_bf16_f32 v91, v88, v89
	v_cvt_pk_bf16_f32 v93, v84, v85
	v_lshl_add_u64 v[94:95], s[94:95], 0, v[106:107]
	v_add_f32_e32 v82, v86, v82
	global_store_dwordx4 v[94:95], v[90:93], off
	v_add_f32_e32 v0, v0, v82
	v_mbcnt_lo_u32_b32 v82, -1, 0
	v_mbcnt_hi_u32_b32 v82, -1, v82
	s_nop 0
	v_lshlrev_b32_e32 v82, 2, v82
	v_xor_b32_e32 v82, 64, v82
	ds_bpermute_b32 v82, v82, v0
	s_waitcnt lgkmcnt(0)
	v_add_f32_e32 v0, v0, v82
	v_mbcnt_lo_u32_b32 v82, -1, 0
	v_mbcnt_hi_u32_b32 v82, -1, v82
	s_nop 0
	v_lshlrev_b32_e32 v82, 2, v82
	v_xor_b32_e32 v82, 0x80, v82
	ds_bpermute_b32 v82, v82, v0
	s_and_saveexec_b64 s[38:39], vcc
	s_cbranch_execz .LBB1_1402
	v_lshlrev_b64 v[84:85], 6, v[98:99]
	v_lshl_add_u64 v[84:85], s[96:97], 0, v[84:85]
	v_lshl_add_u64 v[84:85], s[36:37], 2, v[84:85]
	s_lshl_b32 s40, s49, 2
	s_mov_b32 s41, s76
	v_lshl_add_u64 v[84:85], v[84:85], 0, s[40:41]
	s_waitcnt lgkmcnt(0)
	v_add_f32_e32 v0, v0, v82
	global_store_dword v[84:85], v0, off
; #define EFENCE() asm volatile("" ::: "memory")
; DI float sum4q(float s) { s += shx(s, 16); s += shx(s, 32); return s; }
; DI float sq4(const f32x4& v) { return (v.x * v.x + v.y * v.y) + (v.z * v.z + v.w * v.w); }
; DI u32x4 pk8(const f32x4& a, const f32x4& b) { u32x4 w; w.x = cvtpk(a.x, a.y); w.y = cvtpk(a.z, a.w); w.z = cvtpk(b.x, b.y); w.w = cvtpk(b.z, b.w); return w; }
;     DI void operator()(AccRef acc, const Unit& u, int wr, int wc, int fr, int fq) const {
; #pragma unroll
;         for (int ai = 0; ai < 2; ++ai)
; #pragma unroll
;             for (int m = 0; m < 4; ++m) { if ((m & 1) == 0) EFENCE();
;                 const int row = EROW(u, ai, m); float ss = 0.f;
; #pragma unroll
;                 for (int bj = 0; bj < 2; ++bj) {
;                     const size_t off = (size_t)row * DM + u.pn * 256 + bj * 128 + wc * 32 + 8 * fq;
;                     f32x4 x0 = *(const f32x4*)(xin + off), x1 = *(const f32x4*)(xin + off + 4);
;                     x0 += acc[ai][bj][m][0] * alpha; x1 += acc[ai][bj][m][1] * alpha;
;                     *(f32x4*)(xout + off) = x0; *(f32x4*)(xout + off + 4) = x1;
;                     *(u32x4*)(xb + off) = pk8(x0, x1); ss += sq4(x0) + sq4(x1);
;                 }
;                 ss = sum4q(ss);
;                 if (fq == 0) ssq[(size_t)row * 16 + u.pn * 4 + wc] = ss;
.LBB1_1402:
	s_or_b64 exec, exec, s[38:39]
	s_waitcnt lgkmcnt(0)
	v_or_b32_e32 v82, 48, v130
	v_ashrrev_i32_e32 v83, 31, v82
	v_lshlrev_b64 v[84:85], 10, v[82:83]
	v_lshl_add_u64 v[92:93], v[84:85], 0, v[132:133]
	v_lshlrev_b64 v[94:95], 2, v[92:93]
	v_lshl_add_u64 v[96:97], s[8:9], 0, v[94:95]
	s_waitcnt vmcnt(33)
	v_pk_fma_f32 v[74:75], v[74:75], 0.5, v[200:201] op_sel_hi:[1,0,1]
	s_waitcnt vmcnt(32)
	v_pk_fma_f32 v[80:81], v[80:81], 0.5, v[206:207] op_sel_hi:[1,0,1]
	v_pk_fma_f32 v[78:79], v[78:79], 0.5, v[204:205] op_sel_hi:[1,0,1]
	v_lshl_add_u64 v[88:89], s[16:17], 0, v[94:95]
	v_pk_fma_f32 v[76:77], v[76:77], 0.5, v[202:203] op_sel_hi:[1,0,1]
	global_store_dwordx4 v[88:89], v[78:81], off
	global_store_dwordx4 v[88:89], v[74:77], off offset:16
	v_cvt_pk_bf16_f32 v86, v74, v75
	v_mul_f32_e32 v0, v79, v79
	v_mul_f32_e32 v75, v75, v75
	v_cvt_pk_bf16_f32 v84, v78, v79
	v_lshlrev_b64 v[90:91], 1, v[92:93]
	v_fmac_f32_e32 v0, v78, v78
	v_mul_f32_e32 v78, v81, v81
	v_fmac_f32_e32 v75, v74, v74
	v_mul_f32_e32 v74, v77, v77
	v_cvt_pk_bf16_f32 v85, v80, v81
	v_cvt_pk_bf16_f32 v87, v76, v77
	v_lshl_add_u64 v[92:93], s[94:95], 0, v[90:91]
	v_fmac_f32_e32 v78, v80, v80
	v_fmac_f32_e32 v74, v76, v76
	global_store_dwordx4 v[92:93], v[84:87], off
	v_add_f32_e32 v0, v0, v78
	v_add_f32_e32 v74, v75, v74
	v_add_f32_e32 v0, v0, v74
	v_or_b32_e32 v90, 0x100, v90
	s_waitcnt vmcnt(34)
	v_pk_fma_f32 v[66:67], v[66:67], 0.5, v[208:209] op_sel_hi:[1,0,1]
	s_waitcnt vmcnt(33)
	v_pk_fma_f32 v[72:73], v[72:73], 0.5, v[222:223] op_sel_hi:[1,0,1]
	v_pk_fma_f32 v[70:71], v[70:71], 0.5, v[220:221] op_sel_hi:[1,0,1]
	v_pk_fma_f32 v[68:69], v[68:69], 0.5, v[210:211] op_sel_hi:[1,0,1]
	v_add_u32_e32 v242, 0xb0000, v240
	global_load_dwordx4 v[200:203], v242, s[8:9] offset:16
	global_load_dwordx4 v[204:207], v242, s[8:9] offset:0
	global_load_dwordx4 v[208:211], v242, s[8:9] offset:528
	global_load_dwordx4 v[220:223], v242, s[8:9] offset:512
	global_store_dwordx4 v[88:89], v[70:73], off offset:512
	global_store_dwordx4 v[88:89], v[66:69], off offset:528
	v_cvt_pk_bf16_f32 v74, v70, v71
	v_cvt_pk_bf16_f32 v76, v66, v67
	v_mul_f32_e32 v71, v71, v71
	v_mul_f32_e32 v67, v67, v67
	v_fmac_f32_e32 v71, v70, v70
	v_mul_f32_e32 v70, v73, v73
	v_fmac_f32_e32 v67, v66, v66
	v_mul_f32_e32 v66, v69, v69
	v_fmac_f32_e32 v70, v72, v72
	v_fmac_f32_e32 v66, v68, v68
	v_add_f32_e32 v70, v71, v70
	v_add_f32_e32 v66, v67, v66
	v_cvt_pk_bf16_f32 v75, v72, v73
	v_cvt_pk_bf16_f32 v77, v68, v69
	v_lshl_add_u64 v[78:79], s[94:95], 0, v[90:91]
	v_add_f32_e32 v66, v70, v66
	global_store_dwordx4 v[78:79], v[74:77], off
	v_add_f32_e32 v0, v0, v66
	v_mbcnt_lo_u32_b32 v66, -1, 0
	v_mbcnt_hi_u32_b32 v66, -1, v66
	s_nop 0
	v_lshlrev_b32_e32 v66, 2, v66
	v_xor_b32_e32 v66, 64, v66
	ds_bpermute_b32 v66, v66, v0
	s_waitcnt lgkmcnt(0)
	v_add_f32_e32 v0, v0, v66
	v_mbcnt_lo_u32_b32 v66, -1, 0
	v_mbcnt_hi_u32_b32 v66, -1, v66
	s_nop 0
	v_lshlrev_b32_e32 v66, 2, v66
	v_xor_b32_e32 v66, 0x80, v66
	ds_bpermute_b32 v66, v66, v0
	s_and_saveexec_b64 s[38:39], vcc
	s_cbranch_execz .LBB1_1404
	v_lshlrev_b64 v[68:69], 6, v[82:83]
	v_lshl_add_u64 v[68:69], s[96:97], 0, v[68:69]
	v_lshl_add_u64 v[68:69], s[36:37], 2, v[68:69]
	s_lshl_b32 s40, s49, 2
	s_mov_b32 s41, s76
	v_lshl_add_u64 v[68:69], v[68:69], 0, s[40:41]
	s_waitcnt lgkmcnt(0)
	v_add_f32_e32 v0, v0, v66
	global_store_dword v[68:69], v0, off
.LBB1_1404:
	s_or_b64 exec, exec, s[38:39]
	s_waitcnt lgkmcnt(0)
	v_add_u32_e32 v66, 0x80, v130
	v_ashrrev_i32_e32 v67, 31, v66
	v_lshlrev_b64 v[68:69], 10, v[66:67]
	v_lshl_add_u64 v[76:77], v[68:69], 0, v[132:133]
	v_lshlrev_b64 v[78:79], 2, v[76:77]
	v_lshl_add_u64 v[80:81], s[8:9], 0, v[78:79]
	s_waitcnt vmcnt(36)
	v_pk_fma_f32 v[58:59], v[58:59], 0.5, v[148:149] op_sel_hi:[1,0,1]
	s_waitcnt vmcnt(35)
	v_pk_fma_f32 v[64:65], v[64:65], 0.5, v[154:155] op_sel_hi:[1,0,1]
	v_pk_fma_f32 v[62:63], v[62:63], 0.5, v[152:153] op_sel_hi:[1,0,1]
	v_lshl_add_u64 v[72:73], s[16:17], 0, v[78:79]
	v_pk_fma_f32 v[60:61], v[60:61], 0.5, v[150:151] op_sel_hi:[1,0,1]
	global_store_dwordx4 v[72:73], v[62:65], off
	global_store_dwordx4 v[72:73], v[58:61], off offset:16
	v_cvt_pk_bf16_f32 v70, v58, v59
	v_mul_f32_e32 v0, v63, v63
	v_mul_f32_e32 v59, v59, v59
	v_cvt_pk_bf16_f32 v68, v62, v63
	v_lshlrev_b64 v[74:75], 1, v[76:77]
	v_fmac_f32_e32 v0, v62, v62
	v_mul_f32_e32 v62, v65, v65
	v_fmac_f32_e32 v59, v58, v58
	v_mul_f32_e32 v58, v61, v61
	v_cvt_pk_bf16_f32 v69, v64, v65
	v_cvt_pk_bf16_f32 v71, v60, v61
	v_lshl_add_u64 v[76:77], s[94:95], 0, v[74:75]
	v_fmac_f32_e32 v62, v64, v64
	v_fmac_f32_e32 v58, v60, v60
	global_store_dwordx4 v[76:77], v[68:71], off
	v_add_f32_e32 v0, v0, v62
	v_add_f32_e32 v58, v59, v58
	v_add_f32_e32 v0, v0, v58
	v_or_b32_e32 v74, 0x100, v74
	s_waitcnt vmcnt(37)
	v_pk_fma_f32 v[50:51], v[50:51], 0.5, v[156:157] op_sel_hi:[1,0,1]
	s_waitcnt vmcnt(36)
	v_pk_fma_f32 v[56:57], v[56:57], 0.5, v[162:163] op_sel_hi:[1,0,1]
	v_pk_fma_f32 v[54:55], v[54:55], 0.5, v[160:161] op_sel_hi:[1,0,1]
	v_pk_fma_f32 v[52:53], v[52:53], 0.5, v[158:159] op_sel_hi:[1,0,1]
	global_store_dwordx4 v[72:73], v[54:57], off offset:512
	global_store_dwordx4 v[72:73], v[50:53], off offset:528
	v_cvt_pk_bf16_f32 v58, v54, v55
	v_cvt_pk_bf16_f32 v60, v50, v51
	v_mul_f32_e32 v55, v55, v55
	v_mul_f32_e32 v51, v51, v51
	v_fmac_f32_e32 v55, v54, v54
	v_mul_f32_e32 v54, v57, v57
	v_fmac_f32_e32 v51, v50, v50
	v_mul_f32_e32 v50, v53, v53
	v_fmac_f32_e32 v54, v56, v56
	v_fmac_f32_e32 v50, v52, v52
	v_add_f32_e32 v54, v55, v54
	v_add_f32_e32 v50, v51, v50
	v_cvt_pk_bf16_f32 v59, v56, v57
	v_cvt_pk_bf16_f32 v61, v52, v53
	v_lshl_add_u64 v[62:63], s[94:95], 0, v[74:75]
	v_add_f32_e32 v50, v54, v50
	global_store_dwordx4 v[62:63], v[58:61], off
	v_add_f32_e32 v0, v0, v50
	v_mbcnt_lo_u32_b32 v50, -1, 0
	v_mbcnt_hi_u32_b32 v50, -1, v50
	s_nop 0
	v_lshlrev_b32_e32 v50, 2, v50
	v_xor_b32_e32 v50, 64, v50
	ds_bpermute_b32 v50, v50, v0
	s_waitcnt lgkmcnt(0)
	v_add_f32_e32 v0, v0, v50
	v_mbcnt_lo_u32_b32 v50, -1, 0
	v_mbcnt_hi_u32_b32 v50, -1, v50
	s_nop 0
	v_lshlrev_b32_e32 v50, 2, v50
	v_xor_b32_e32 v50, 0x80, v50
	ds_bpermute_b32 v50, v50, v0
	s_and_saveexec_b64 s[38:39], vcc
	s_cbranch_execz .LBB1_1406
	v_lshlrev_b64 v[52:53], 6, v[66:67]
	v_lshl_add_u64 v[52:53], s[96:97], 0, v[52:53]
	v_lshl_add_u64 v[52:53], s[36:37], 2, v[52:53]
	s_lshl_b32 s40, s49, 2
	s_mov_b32 s41, s76
	v_lshl_add_u64 v[52:53], v[52:53], 0, s[40:41]
	s_waitcnt lgkmcnt(0)
	v_add_f32_e32 v0, v0, v50
	global_store_dword v[52:53], v0, off
; #define EFENCE() asm volatile("" ::: "memory")
; DI float sum4q(float s) { s += shx(s, 16); s += shx(s, 32); return s; }
; DI float sq4(const f32x4& v) { return (v.x * v.x + v.y * v.y) + (v.z * v.z + v.w * v.w); }
; DI u32x4 pk8(const f32x4& a, const f32x4& b) { u32x4 w; w.x = cvtpk(a.x, a.y); w.y = cvtpk(a.z, a.w); w.z = cvtpk(b.x, b.y); w.w = cvtpk(b.z, b.w); return w; }
;     DI void operator()(AccRef acc, const Unit& u, int wr, int wc, int fr, int fq) const {
; #pragma unroll
;         for (int ai = 0; ai < 2; ++ai)
; #pragma unroll
;             for (int m = 0; m < 4; ++m) { if ((m & 1) == 0) EFENCE();
;                 const int row = EROW(u, ai, m); float ss = 0.f;
; #pragma unroll
;                 for (int bj = 0; bj < 2; ++bj) {
;                     const size_t off = (size_t)row * DM + u.pn * 256 + bj * 128 + wc * 32 + 8 * fq;
;                     f32x4 x0 = *(const f32x4*)(xin + off), x1 = *(const f32x4*)(xin + off + 4);
;                     x0 += acc[ai][bj][m][0] * alpha; x1 += acc[ai][bj][m][1] * alpha;
;                     *(f32x4*)(xout + off) = x0; *(f32x4*)(xout + off + 4) = x1;
;                     *(u32x4*)(xb + off) = pk8(x0, x1); ss += sq4(x0) + sq4(x1);
;                 }
;                 ss = sum4q(ss);
;                 if (fq == 0) ssq[(size_t)row * 16 + u.pn * 4 + wc] = ss;
.LBB1_1406:
	s_or_b64 exec, exec, s[38:39]
	s_waitcnt lgkmcnt(0)
	v_add_u32_e32 v50, 0x90, v130
	v_ashrrev_i32_e32 v51, 31, v50
	v_lshlrev_b64 v[52:53], 10, v[50:51]
	v_lshl_add_u64 v[60:61], v[52:53], 0, v[132:133]
	v_lshlrev_b64 v[62:63], 2, v[60:61]
	v_lshl_add_u64 v[64:65], s[8:9], 0, v[62:63]
	s_waitcnt vmcnt(32)
	v_pk_fma_f32 v[42:43], v[42:43], 0.5, v[164:165] op_sel_hi:[1,0,1]
	s_waitcnt vmcnt(31)
	v_pk_fma_f32 v[48:49], v[48:49], 0.5, v[170:171] op_sel_hi:[1,0,1]
	v_pk_fma_f32 v[46:47], v[46:47], 0.5, v[168:169] op_sel_hi:[1,0,1]
	v_lshl_add_u64 v[56:57], s[16:17], 0, v[62:63]
	v_pk_fma_f32 v[44:45], v[44:45], 0.5, v[166:167] op_sel_hi:[1,0,1]
	global_store_dwordx4 v[56:57], v[46:49], off
	global_store_dwordx4 v[56:57], v[42:45], off offset:16
	v_cvt_pk_bf16_f32 v54, v42, v43
	v_mul_f32_e32 v0, v47, v47
	v_mul_f32_e32 v43, v43, v43
	v_cvt_pk_bf16_f32 v52, v46, v47
	v_lshlrev_b64 v[58:59], 1, v[60:61]
	v_fmac_f32_e32 v0, v46, v46
	v_mul_f32_e32 v46, v49, v49
	v_fmac_f32_e32 v43, v42, v42
	v_mul_f32_e32 v42, v45, v45
	v_cvt_pk_bf16_f32 v53, v48, v49
	v_cvt_pk_bf16_f32 v55, v44, v45
	v_lshl_add_u64 v[60:61], s[94:95], 0, v[58:59]
	v_fmac_f32_e32 v46, v48, v48
	v_fmac_f32_e32 v42, v44, v44
	global_store_dwordx4 v[60:61], v[52:55], off
	v_add_f32_e32 v0, v0, v46
	v_add_f32_e32 v42, v43, v42
	v_add_f32_e32 v0, v0, v42
	v_or_b32_e32 v58, 0x100, v58
	s_waitcnt vmcnt(33)
	v_pk_fma_f32 v[34:35], v[34:35], 0.5, v[172:173] op_sel_hi:[1,0,1]
	s_waitcnt vmcnt(32)
	v_pk_fma_f32 v[40:41], v[40:41], 0.5, v[182:183] op_sel_hi:[1,0,1]
	v_pk_fma_f32 v[38:39], v[38:39], 0.5, v[180:181] op_sel_hi:[1,0,1]
	v_pk_fma_f32 v[36:37], v[36:37], 0.5, v[174:175] op_sel_hi:[1,0,1]
	global_store_dwordx4 v[56:57], v[38:41], off offset:512
	global_store_dwordx4 v[56:57], v[34:37], off offset:528
	v_cvt_pk_bf16_f32 v42, v38, v39
	v_cvt_pk_bf16_f32 v44, v34, v35
	v_mul_f32_e32 v39, v39, v39
	v_mul_f32_e32 v35, v35, v35
	v_fmac_f32_e32 v39, v38, v38
	v_mul_f32_e32 v38, v41, v41
	v_fmac_f32_e32 v35, v34, v34
	v_mul_f32_e32 v34, v37, v37
	v_fmac_f32_e32 v38, v40, v40
	v_fmac_f32_e32 v34, v36, v36
	v_add_f32_e32 v38, v39, v38
	v_add_f32_e32 v34, v35, v34
	v_cvt_pk_bf16_f32 v43, v40, v41
	v_cvt_pk_bf16_f32 v45, v36, v37
	v_lshl_add_u64 v[46:47], s[94:95], 0, v[58:59]
	v_add_f32_e32 v34, v38, v34
	global_store_dwordx4 v[46:47], v[42:45], off
	v_add_f32_e32 v0, v0, v34
	v_mbcnt_lo_u32_b32 v34, -1, 0
	v_mbcnt_hi_u32_b32 v34, -1, v34
	s_nop 0
	v_lshlrev_b32_e32 v34, 2, v34
	v_xor_b32_e32 v34, 64, v34
	ds_bpermute_b32 v34, v34, v0
	s_waitcnt lgkmcnt(0)
	v_add_f32_e32 v0, v0, v34
	v_mbcnt_lo_u32_b32 v34, -1, 0
	v_mbcnt_hi_u32_b32 v34, -1, v34
	s_nop 0
	v_lshlrev_b32_e32 v34, 2, v34
	v_xor_b32_e32 v34, 0x80, v34
	ds_bpermute_b32 v34, v34, v0
	s_and_saveexec_b64 s[38:39], vcc
	s_cbranch_execz .LBB1_1408
	v_lshlrev_b64 v[36:37], 6, v[50:51]
	v_lshl_add_u64 v[36:37], s[96:97], 0, v[36:37]
	v_lshl_add_u64 v[36:37], s[36:37], 2, v[36:37]
	s_lshl_b32 s40, s49, 2
	s_mov_b32 s41, s76
	v_lshl_add_u64 v[36:37], v[36:37], 0, s[40:41]
	s_waitcnt lgkmcnt(0)
	v_add_f32_e32 v0, v0, v34
	global_store_dword v[36:37], v0, off
; #define EFENCE() asm volatile("" ::: "memory")
; DI float sum4q(float s) { s += shx(s, 16); s += shx(s, 32); return s; }
; DI float sq4(const f32x4& v) { return (v.x * v.x + v.y * v.y) + (v.z * v.z + v.w * v.w); }
; DI u32x4 pk8(const f32x4& a, const f32x4& b) { u32x4 w; w.x = cvtpk(a.x, a.y); w.y = cvtpk(a.z, a.w); w.z = cvtpk(b.x, b.y); w.w = cvtpk(b.z, b.w); return w; }
;     DI void operator()(AccRef acc, const Unit& u, int wr, int wc, int fr, int fq) const {
; #pragma unroll
;         for (int ai = 0; ai < 2; ++ai)
; #pragma unroll
;             for (int m = 0; m < 4; ++m) { if ((m & 1) == 0) EFENCE();
;                 const int row = EROW(u, ai, m); float ss = 0.f;
; #pragma unroll
;                 for (int bj = 0; bj < 2; ++bj) {
;                     const size_t off = (size_t)row * DM + u.pn * 256 + bj * 128 + wc * 32 + 8 * fq;
;                     f32x4 x0 = *(const f32x4*)(xin + off), x1 = *(const f32x4*)(xin + off + 4);
;                     x0 += acc[ai][bj][m][0] * alpha; x1 += acc[ai][bj][m][1] * alpha;
;                     *(f32x4*)(xout + off) = x0; *(f32x4*)(xout + off + 4) = x1;
;                     *(u32x4*)(xb + off) = pk8(x0, x1); ss += sq4(x0) + sq4(x1);
;                 }
;                 ss = sum4q(ss);
;                 if (fq == 0) ssq[(size_t)row * 16 + u.pn * 4 + wc] = ss;
.LBB1_1408:
	s_or_b64 exec, exec, s[38:39]
	s_waitcnt lgkmcnt(0)
	v_add_u32_e32 v34, 0xa0, v130
	v_ashrrev_i32_e32 v35, 31, v34
	v_lshlrev_b64 v[36:37], 10, v[34:35]
	v_lshl_add_u64 v[44:45], v[36:37], 0, v[132:133]
	v_lshlrev_b64 v[46:47], 2, v[44:45]
	v_lshl_add_u64 v[48:49], s[8:9], 0, v[46:47]
	s_waitcnt vmcnt(28)
	v_pk_fma_f32 v[26:27], v[26:27], 0.5, v[184:185] op_sel_hi:[1,0,1]
	s_waitcnt vmcnt(27)
	v_pk_fma_f32 v[32:33], v[32:33], 0.5, v[190:191] op_sel_hi:[1,0,1]
	v_pk_fma_f32 v[30:31], v[30:31], 0.5, v[188:189] op_sel_hi:[1,0,1]
	v_lshl_add_u64 v[40:41], s[16:17], 0, v[46:47]
	v_pk_fma_f32 v[28:29], v[28:29], 0.5, v[186:187] op_sel_hi:[1,0,1]
	global_store_dwordx4 v[40:41], v[30:33], off
	global_store_dwordx4 v[40:41], v[26:29], off offset:16
	v_cvt_pk_bf16_f32 v38, v26, v27
	v_mul_f32_e32 v0, v31, v31
	v_mul_f32_e32 v27, v27, v27
	v_cvt_pk_bf16_f32 v36, v30, v31
	v_lshlrev_b64 v[42:43], 1, v[44:45]
	v_fmac_f32_e32 v0, v30, v30
	v_mul_f32_e32 v30, v33, v33
	v_fmac_f32_e32 v27, v26, v26
	v_mul_f32_e32 v26, v29, v29
	v_cvt_pk_bf16_f32 v37, v32, v33
	v_cvt_pk_bf16_f32 v39, v28, v29
	v_lshl_add_u64 v[44:45], s[94:95], 0, v[42:43]
	v_fmac_f32_e32 v30, v32, v32
	v_fmac_f32_e32 v26, v28, v28
	global_store_dwordx4 v[44:45], v[36:39], off
	v_add_f32_e32 v0, v0, v30
	v_add_f32_e32 v26, v27, v26
	v_add_f32_e32 v0, v0, v26
	v_or_b32_e32 v42, 0x100, v42
	s_waitcnt vmcnt(29)
	v_pk_fma_f32 v[18:19], v[18:19], 0.5, v[192:193] op_sel_hi:[1,0,1]
	s_waitcnt vmcnt(28)
	v_pk_fma_f32 v[24:25], v[24:25], 0.5, v[198:199] op_sel_hi:[1,0,1]
	v_pk_fma_f32 v[22:23], v[22:23], 0.5, v[196:197] op_sel_hi:[1,0,1]
	v_pk_fma_f32 v[20:21], v[20:21], 0.5, v[194:195] op_sel_hi:[1,0,1]
	global_store_dwordx4 v[40:41], v[22:25], off offset:512
	global_store_dwordx4 v[40:41], v[18:21], off offset:528
	v_cvt_pk_bf16_f32 v26, v22, v23
	v_cvt_pk_bf16_f32 v28, v18, v19
	v_mul_f32_e32 v23, v23, v23
	v_mul_f32_e32 v19, v19, v19
	v_fmac_f32_e32 v23, v22, v22
	v_mul_f32_e32 v22, v25, v25
	v_fmac_f32_e32 v19, v18, v18
	v_mul_f32_e32 v18, v21, v21
	v_fmac_f32_e32 v22, v24, v24
	v_fmac_f32_e32 v18, v20, v20
	v_add_f32_e32 v22, v23, v22
	v_add_f32_e32 v18, v19, v18
	v_cvt_pk_bf16_f32 v27, v24, v25
	v_cvt_pk_bf16_f32 v29, v20, v21
	v_lshl_add_u64 v[30:31], s[94:95], 0, v[42:43]
	v_add_f32_e32 v18, v22, v18
	global_store_dwordx4 v[30:31], v[26:29], off
	v_add_f32_e32 v0, v0, v18
	v_mbcnt_lo_u32_b32 v18, -1, 0
	v_mbcnt_hi_u32_b32 v18, -1, v18
	s_nop 0
	v_lshlrev_b32_e32 v18, 2, v18
	v_xor_b32_e32 v18, 64, v18
	ds_bpermute_b32 v18, v18, v0
	s_waitcnt lgkmcnt(0)
	v_add_f32_e32 v0, v0, v18
	v_mbcnt_lo_u32_b32 v18, -1, 0
	v_mbcnt_hi_u32_b32 v18, -1, v18
	s_nop 0
	v_lshlrev_b32_e32 v18, 2, v18
	v_xor_b32_e32 v18, 0x80, v18
	ds_bpermute_b32 v18, v18, v0
	s_and_saveexec_b64 s[38:39], vcc
	s_cbranch_execz .LBB1_1410
	v_lshlrev_b64 v[20:21], 6, v[34:35]
	v_lshl_add_u64 v[20:21], s[96:97], 0, v[20:21]
	v_lshl_add_u64 v[20:21], s[36:37], 2, v[20:21]
	s_lshl_b32 s40, s49, 2
	s_mov_b32 s41, s76
	v_lshl_add_u64 v[20:21], v[20:21], 0, s[40:41]
	s_waitcnt lgkmcnt(0)
	v_add_f32_e32 v0, v0, v18
	global_store_dword v[20:21], v0, off
.LBB1_1410:
	s_or_b64 exec, exec, s[38:39]
	s_waitcnt lgkmcnt(0)
	v_add_u32_e32 v18, 0xb0, v130
	v_ashrrev_i32_e32 v19, 31, v18
	v_lshlrev_b64 v[20:21], 10, v[18:19]
	v_lshl_add_u64 v[28:29], v[20:21], 0, v[132:133]
	v_lshlrev_b64 v[30:31], 2, v[28:29]
	v_lshl_add_u64 v[32:33], s[8:9], 0, v[30:31]
	s_waitcnt vmcnt(24)
	v_pk_fma_f32 v[10:11], v[10:11], 0.5, v[200:201] op_sel_hi:[1,0,1]
	s_waitcnt vmcnt(23)
	v_pk_fma_f32 v[16:17], v[16:17], 0.5, v[206:207] op_sel_hi:[1,0,1]
	v_pk_fma_f32 v[14:15], v[14:15], 0.5, v[204:205] op_sel_hi:[1,0,1]
	v_lshl_add_u64 v[24:25], s[16:17], 0, v[30:31]
	v_pk_fma_f32 v[12:13], v[12:13], 0.5, v[202:203] op_sel_hi:[1,0,1]
	global_store_dwordx4 v[24:25], v[14:17], off
	global_store_dwordx4 v[24:25], v[10:13], off offset:16
	v_cvt_pk_bf16_f32 v22, v10, v11
	v_mul_f32_e32 v0, v15, v15
	v_mul_f32_e32 v11, v11, v11
	v_cvt_pk_bf16_f32 v20, v14, v15
	v_lshlrev_b64 v[26:27], 1, v[28:29]
	v_fmac_f32_e32 v0, v14, v14
	v_mul_f32_e32 v14, v17, v17
	v_fmac_f32_e32 v11, v10, v10
	v_mul_f32_e32 v10, v13, v13
	v_cvt_pk_bf16_f32 v21, v16, v17
	v_cvt_pk_bf16_f32 v23, v12, v13
	v_lshl_add_u64 v[28:29], s[94:95], 0, v[26:27]
	v_fmac_f32_e32 v14, v16, v16
	v_fmac_f32_e32 v10, v12, v12
	global_store_dwordx4 v[28:29], v[20:23], off
	v_add_f32_e32 v0, v0, v14
	v_add_f32_e32 v10, v11, v10
	v_add_f32_e32 v0, v0, v10
	v_or_b32_e32 v26, 0x100, v26
	s_waitcnt vmcnt(25)
	v_pk_fma_f32 v[2:3], v[2:3], 0.5, v[208:209] op_sel_hi:[1,0,1]
	s_waitcnt vmcnt(24)
	v_pk_fma_f32 v[8:9], v[8:9], 0.5, v[222:223] op_sel_hi:[1,0,1]
	v_pk_fma_f32 v[6:7], v[6:7], 0.5, v[220:221] op_sel_hi:[1,0,1]
	v_pk_fma_f32 v[4:5], v[4:5], 0.5, v[210:211] op_sel_hi:[1,0,1]
	global_store_dwordx4 v[24:25], v[6:9], off offset:512
	global_store_dwordx4 v[24:25], v[2:5], off offset:528
	v_cvt_pk_bf16_f32 v10, v6, v7
	v_cvt_pk_bf16_f32 v12, v2, v3
	v_mul_f32_e32 v7, v7, v7
	v_mul_f32_e32 v3, v3, v3
	v_fmac_f32_e32 v7, v6, v6
	v_mul_f32_e32 v6, v9, v9
	v_fmac_f32_e32 v3, v2, v2
	v_mul_f32_e32 v2, v5, v5
	v_fmac_f32_e32 v6, v8, v8
	v_fmac_f32_e32 v2, v4, v4
	v_add_f32_e32 v6, v7, v6
	v_add_f32_e32 v2, v3, v2
	v_cvt_pk_bf16_f32 v11, v8, v9
	v_cvt_pk_bf16_f32 v13, v4, v5
	v_lshl_add_u64 v[14:15], s[94:95], 0, v[26:27]
	v_add_f32_e32 v2, v6, v2
	global_store_dwordx4 v[14:15], v[10:13], off
	v_add_f32_e32 v0, v0, v2
	v_mbcnt_lo_u32_b32 v2, -1, 0
	v_mbcnt_hi_u32_b32 v2, -1, v2
	s_nop 0
	v_lshlrev_b32_e32 v2, 2, v2
	v_xor_b32_e32 v2, 64, v2
	ds_bpermute_b32 v2, v2, v0
	s_waitcnt lgkmcnt(0)
	v_add_f32_e32 v0, v0, v2
	v_mbcnt_lo_u32_b32 v2, -1, 0
	v_mbcnt_hi_u32_b32 v2, -1, v2
	s_nop 0
	v_lshlrev_b32_e32 v2, 2, v2
	v_xor_b32_e32 v2, 0x80, v2
	ds_bpermute_b32 v2, v2, v0
	s_and_saveexec_b64 s[38:39], vcc
	s_cbranch_execz .LBB1_1412
	v_lshlrev_b64 v[4:5], 6, v[18:19]
	v_lshl_add_u64 v[4:5], s[96:97], 0, v[4:5]
	v_lshl_add_u64 v[4:5], s[36:37], 2, v[4:5]
	s_lshl_b32 s36, s49, 2
	s_mov_b32 s37, s76
	v_lshl_add_u64 v[4:5], v[4:5], 0, s[36:37]
	s_waitcnt lgkmcnt(0)
	v_add_f32_e32 v0, v0, v2
	global_store_dword v[4:5], v0, off
